# attention: the six half-wave (lane^32) exchanges (row ssq / max / sum) use v_permlane32_swap on two copies + commutative consumer instead of ds_bpermute + LDS wait
# speedup vs baseline: 1.0061x; 1.0018x over previous
.LBB0_347:
	v_cndmask_b32_e64 v72, v48, v212, s[2:3]
	v_cndmask_b32_e64 v167, v72, v48, s[4:5]
	v_max3_f32 v48, v98, s64, v105
	v_max3_f32 v48, v48, v104, v103
	v_max3_f32 v48, v48, v102, v101
	v_max3_f32 v48, v48, v100, v99
	v_max3_f32 v48, v48, v71, v70
	v_max3_f32 v48, v48, v69, v68
	v_max3_f32 v48, v48, v67, v66
	v_max3_f32 v48, v48, v65, v64
	v_max3_f32 v48, v48, v32, v33
	v_max3_f32 v48, v48, v34, v35
	v_max3_f32 v48, v48, v36, v37
	v_max3_f32 v48, v48, v38, v39
	v_max3_f32 v48, v48, v40, v41
	v_max3_f32 v48, v48, v42, v43
	v_max3_f32 v48, v48, v44, v45
	v_max3_f32 v48, v48, v46, v47
	v_max3_f32 v48, v48, v16, v17
	v_max3_f32 v48, v48, v18, v19
	v_max3_f32 v48, v48, v20, v21
	v_max3_f32 v48, v48, v22, v23
	v_max3_f32 v48, v48, v24, v25
	v_max3_f32 v48, v48, v26, v27
	v_max3_f32 v48, v48, v28, v29
	v_max3_f32 v48, v48, v30, v31
	v_max3_f32 v48, v48, v0, v1
	v_max3_f32 v48, v48, v2, v3
	v_max3_f32 v48, v48, v4, v5
	v_max3_f32 v48, v48, v6, v7
	v_max3_f32 v48, v48, v8, v9
	v_max3_f32 v48, v48, v10, v11
	v_max3_f32 v48, v48, v12, v13
	v_cndmask_b32_e64 v166, v212, v49, s[4:5]
	v_max3_f32 v48, v48, v14, v15
	v_cndmask_b32_e64 v168, v50, v212, s[6:7]
	v_cndmask_b32_e64 v169, v51, v212, s[8:9]
	v_max3_f32 v48, v48, v167, v166
	v_cndmask_b32_e64 v170, v52, v212, s[10:11]
	v_cndmask_b32_e64 v171, v53, v212, s[12:13]
	v_max3_f32 v48, v48, v168, v169
	v_cndmask_b32_e64 v172, v54, v212, s[14:15]
	v_cndmask_b32_e64 v173, v55, v212, s[16:17]
	v_max3_f32 v48, v48, v170, v171
	v_cndmask_b32_e64 v174, v56, v212, s[18:19]
	v_cndmask_b32_e64 v175, v57, v212, s[20:21]
	v_max3_f32 v48, v48, v172, v173
	v_cndmask_b32_e64 v176, v58, v212, s[22:23]
	v_cndmask_b32_e64 v177, v59, v212, s[24:25]
	v_max3_f32 v48, v48, v174, v175
	v_cndmask_b32_e64 v178, v60, v212, s[26:27]
	v_cndmask_b32_e64 v179, v61, v212, s[28:29]
	v_max3_f32 v48, v48, v176, v177
	v_cndmask_b32_e64 v180, v62, v212, s[30:31]
	v_cndmask_b32_e64 v181, v63, v212, s[34:35]
	v_max3_f32 v48, v48, v178, v179
	v_max3_f32 v48, v48, v180, v181
	v_mov_b32_e32 v142, v48
	v_mov_b32_e32 v143, v48
	s_nop 1
	v_permlane32_swap_b32_e32 v142, v143
	v_or_b32_e32 v153, s89, v118
	v_readlane_b32 s0, v255, 16
	s_add_i32 s96, s96, s1
	s_add_i32 s90, s90, s0
	s_waitcnt lgkmcnt(0)
	v_max3_f32 v213, v142, v143, v96
	v_sub_f32_e32 v50, v104, v213
	v_exp_f32_e32 v154, v50
	v_sub_f32_e32 v50, v103, v213
	v_exp_f32_e32 v155, v50
	v_sub_f32_e32 v50, v102, v213
	v_exp_f32_e32 v160, v50
	v_sub_f32_e32 v50, v101, v213
	v_exp_f32_e32 v161, v50
	v_sub_f32_e32 v50, v100, v213
	v_sub_f32_e32 v48, v98, v213
	v_exp_f32_e32 v164, v50
	v_sub_f32_e32 v50, v99, v213
	v_exp_f32_e32 v110, v48
	v_sub_f32_e32 v48, v105, v213
	v_exp_f32_e32 v165, v50
	v_sub_f32_e32 v50, v71, v213
	v_exp_f32_e32 v111, v48
	v_exp_f32_e32 v102, v50
	v_sub_f32_e32 v50, v70, v213
	v_exp_f32_e32 v103, v50
	v_pk_add_f32 v[232:233], v[68:69], v[212:213] op_sel:[0,1] op_sel_hi:[1,1] neg_lo:[0,1] neg_hi:[0,1]
	v_pk_add_f32 v[234:235], v[34:35], v[212:213] op_sel:[0,1] op_sel_hi:[1,1] neg_lo:[0,1] neg_hi:[0,1]
	v_exp_f32_e32 v112, v233
	v_exp_f32_e32 v106, v234
	v_exp_f32_e32 v113, v232
	v_pk_add_f32 v[232:233], v[66:67], v[212:213] op_sel:[0,1] op_sel_hi:[1,1] neg_lo:[0,1] neg_hi:[0,1]
	v_exp_f32_e32 v107, v235
	v_pk_add_f32 v[234:235], v[36:37], v[212:213] op_sel:[0,1] op_sel_hi:[1,1] neg_lo:[0,1] neg_hi:[0,1]
	v_pk_add_f32 v[48:49], v[110:111], 0 op_sel_hi:[1,0]
	v_exp_f32_e32 v156, v233
	v_exp_f32_e32 v118, v234
	v_pk_add_f32 v[48:49], v[154:155], v[48:49]
	v_exp_f32_e32 v157, v232
	v_pk_add_f32 v[232:233], v[64:65], v[212:213] op_sel:[0,1] op_sel_hi:[1,1] neg_lo:[0,1] neg_hi:[0,1]
	v_exp_f32_e32 v119, v235
	v_pk_add_f32 v[234:235], v[38:39], v[212:213] op_sel:[0,1] op_sel_hi:[1,1] neg_lo:[0,1] neg_hi:[0,1]
	v_pk_add_f32 v[48:49], v[160:161], v[48:49]
	v_exp_f32_e32 v162, v233
	v_pk_add_f32 v[236:237], v[32:33], v[212:213] op_sel:[0,1] op_sel_hi:[1,1] neg_lo:[0,1] neg_hi:[0,1]
	v_exp_f32_e32 v158, v234
	v_pk_add_f32 v[48:49], v[164:165], v[48:49]
	v_exp_f32_e32 v163, v232
	v_exp_f32_e32 v78, v236
	v_exp_f32_e32 v159, v235
	v_pk_add_f32 v[232:233], v[40:41], v[212:213] op_sel:[0,1] op_sel_hi:[1,1] neg_lo:[0,1] neg_hi:[0,1]
	v_pk_add_f32 v[48:49], v[102:103], v[48:49]
	v_exp_f32_e32 v79, v237
	v_exp_f32_e32 v68, v232
	v_pk_add_f32 v[48:49], v[112:113], v[48:49]
	v_exp_f32_e32 v69, v233
	v_pk_add_f32 v[232:233], v[42:43], v[212:213] op_sel:[0,1] op_sel_hi:[1,1] neg_lo:[0,1] neg_hi:[0,1]
	v_pk_add_f32 v[234:235], v[18:19], v[212:213] op_sel:[0,1] op_sel_hi:[1,1] neg_lo:[0,1] neg_hi:[0,1]
	v_pk_add_f32 v[236:237], v[2:3], v[212:213] op_sel:[0,1] op_sel_hi:[1,1] neg_lo:[0,1] neg_hi:[0,1]
	v_pk_add_f32 v[48:49], v[156:157], v[48:49]
	v_exp_f32_e32 v76, v232
	v_exp_f32_e32 v72, v234
	v_exp_f32_e32 v60, v236
	v_pk_add_f32 v[48:49], v[162:163], v[48:49]
	v_exp_f32_e32 v77, v233
	v_pk_add_f32 v[232:233], v[44:45], v[212:213] op_sel:[0,1] op_sel_hi:[1,1] neg_lo:[0,1] neg_hi:[0,1]
	v_exp_f32_e32 v73, v235
	v_pk_add_f32 v[234:235], v[20:21], v[212:213] op_sel:[0,1] op_sel_hi:[1,1] neg_lo:[0,1] neg_hi:[0,1]
	v_exp_f32_e32 v61, v237
	v_pk_add_f32 v[236:237], v[4:5], v[212:213] op_sel:[0,1] op_sel_hi:[1,1] neg_lo:[0,1] neg_hi:[0,1]
	v_pk_add_f32 v[32:33], v[78:79], v[48:49]
	v_exp_f32_e32 v104, v232
	v_exp_f32_e32 v100, v234
	v_exp_f32_e32 v66, v236
	v_pk_add_f32 v[32:33], v[106:107], v[32:33]
	v_exp_f32_e32 v105, v233
	v_pk_add_f32 v[232:233], v[46:47], v[212:213] op_sel:[0,1] op_sel_hi:[1,1] neg_lo:[0,1] neg_hi:[0,1]
	v_exp_f32_e32 v101, v235
	v_pk_add_f32 v[234:235], v[22:23], v[212:213] op_sel:[0,1] op_sel_hi:[1,1] neg_lo:[0,1] neg_hi:[0,1]
	v_exp_f32_e32 v67, v237
	v_pk_add_f32 v[236:237], v[6:7], v[212:213] op_sel:[0,1] op_sel_hi:[1,1] neg_lo:[0,1] neg_hi:[0,1]
	v_pk_add_f32 v[32:33], v[118:119], v[32:33]
	v_exp_f32_e32 v114, v232
	v_pk_add_f32 v[238:239], v[16:17], v[212:213] op_sel:[0,1] op_sel_hi:[1,1] neg_lo:[0,1] neg_hi:[0,1]
	v_exp_f32_e32 v108, v234
	v_exp_f32_e32 v74, v236
	v_pk_add_f32 v[32:33], v[158:159], v[32:33]
	v_exp_f32_e32 v115, v233
	v_exp_f32_e32 v64, v238
	v_exp_f32_e32 v109, v235
	v_pk_add_f32 v[232:233], v[24:25], v[212:213] op_sel:[0,1] op_sel_hi:[1,1] neg_lo:[0,1] neg_hi:[0,1]
	v_exp_f32_e32 v75, v237
	v_pk_add_f32 v[234:235], v[8:9], v[212:213] op_sel:[0,1] op_sel_hi:[1,1] neg_lo:[0,1] neg_hi:[0,1]
	v_pk_add_f32 v[32:33], v[68:69], v[32:33]
	v_exp_f32_e32 v65, v239
	v_exp_f32_e32 v58, v232
	v_exp_f32_e32 v48, v234
	v_pk_add_f32 v[32:33], v[76:77], v[32:33]
	v_exp_f32_e32 v59, v233
	v_pk_add_f32 v[232:233], v[26:27], v[212:213] op_sel:[0,1] op_sel_hi:[1,1] neg_lo:[0,1] neg_hi:[0,1]
	v_exp_f32_e32 v49, v235
	v_pk_add_f32 v[234:235], v[10:11], v[212:213] op_sel:[0,1] op_sel_hi:[1,1] neg_lo:[0,1] neg_hi:[0,1]
	v_pk_add_f32 v[32:33], v[104:105], v[32:33]
	v_exp_f32_e32 v62, v232
	v_exp_f32_e32 v50, v234
	v_pk_add_f32 v[32:33], v[114:115], v[32:33]
	v_exp_f32_e32 v63, v233
	v_pk_add_f32 v[232:233], v[28:29], v[212:213] op_sel:[0,1] op_sel_hi:[1,1] neg_lo:[0,1] neg_hi:[0,1]
	v_exp_f32_e32 v51, v235
	v_pk_add_f32 v[234:235], v[12:13], v[212:213] op_sel:[0,1] op_sel_hi:[1,1] neg_lo:[0,1] neg_hi:[0,1]
	v_pk_add_f32 v[16:17], v[64:65], v[32:33]
	v_exp_f32_e32 v70, v232
	v_exp_f32_e32 v52, v234
	v_pk_add_f32 v[16:17], v[72:73], v[16:17]
	v_exp_f32_e32 v71, v233
	v_pk_add_f32 v[232:233], v[30:31], v[212:213] op_sel:[0,1] op_sel_hi:[1,1] neg_lo:[0,1] neg_hi:[0,1]
	v_exp_f32_e32 v53, v235
	v_pk_add_f32 v[234:235], v[14:15], v[212:213] op_sel:[0,1] op_sel_hi:[1,1] neg_lo:[0,1] neg_hi:[0,1]
	v_pk_add_f32 v[16:17], v[100:101], v[16:17]
	v_exp_f32_e32 v98, v232
	v_pk_add_f32 v[236:237], v[0:1], v[212:213] op_sel:[0,1] op_sel_hi:[1,1] neg_lo:[0,1] neg_hi:[0,1]
	v_exp_f32_e32 v54, v234
	v_pk_add_f32 v[16:17], v[108:109], v[16:17]
	v_exp_f32_e32 v99, v233
	v_exp_f32_e32 v56, v236
	v_exp_f32_e32 v55, v235
	v_pk_add_f32 v[232:233], v[166:167], v[212:213] op_sel:[0,1] op_sel_hi:[1,1] neg_lo:[0,1] neg_hi:[0,1]
	v_pk_add_f32 v[16:17], v[58:59], v[16:17]
	v_exp_f32_e32 v57, v237
	v_exp_f32_e32 v40, v233
	v_pk_add_f32 v[16:17], v[62:63], v[16:17]
	v_exp_f32_e32 v41, v232
	v_pk_add_f32 v[232:233], v[168:169], v[212:213] op_sel:[0,1] op_sel_hi:[1,1] neg_lo:[0,1] neg_hi:[0,1]
	v_pk_add_f32 v[16:17], v[70:71], v[16:17]
	v_exp_f32_e32 v42, v232
	v_pk_add_f32 v[16:17], v[98:99], v[16:17]
	v_exp_f32_e32 v43, v233
	v_pk_add_f32 v[232:233], v[170:171], v[212:213] op_sel:[0,1] op_sel_hi:[1,1] neg_lo:[0,1] neg_hi:[0,1]
	v_pk_add_f32 v[0:1], v[56:57], v[16:17]
	v_exp_f32_e32 v44, v232
	v_pk_add_f32 v[0:1], v[60:61], v[0:1]
	v_exp_f32_e32 v45, v233
	v_pk_add_f32 v[232:233], v[172:173], v[212:213] op_sel:[0,1] op_sel_hi:[1,1] neg_lo:[0,1] neg_hi:[0,1]
	v_pk_add_f32 v[0:1], v[66:67], v[0:1]
	v_exp_f32_e32 v46, v232
	v_pk_add_f32 v[0:1], v[74:75], v[0:1]
	v_exp_f32_e32 v47, v233
	v_pk_add_f32 v[232:233], v[174:175], v[212:213] op_sel:[0,1] op_sel_hi:[1,1] neg_lo:[0,1] neg_hi:[0,1]
	v_pk_add_f32 v[0:1], v[48:49], v[0:1]
	v_exp_f32_e32 v32, v232
	v_pk_add_f32 v[0:1], v[50:51], v[0:1]
	v_exp_f32_e32 v33, v233
	v_pk_add_f32 v[232:233], v[176:177], v[212:213] op_sel:[0,1] op_sel_hi:[1,1] neg_lo:[0,1] neg_hi:[0,1]
	v_pk_add_f32 v[0:1], v[52:53], v[0:1]
	v_exp_f32_e32 v34, v232
	v_pk_add_f32 v[0:1], v[54:55], v[0:1]
	v_exp_f32_e32 v35, v233
	v_pk_add_f32 v[232:233], v[178:179], v[212:213] op_sel:[0,1] op_sel_hi:[1,1] neg_lo:[0,1] neg_hi:[0,1]
	v_pk_add_f32 v[0:1], v[40:41], v[0:1]
	v_exp_f32_e32 v36, v232
	v_pk_add_f32 v[0:1], v[42:43], v[0:1]
	v_exp_f32_e32 v37, v233
	v_pk_add_f32 v[232:233], v[180:181], v[212:213] op_sel:[0,1] op_sel_hi:[1,1] neg_lo:[0,1] neg_hi:[0,1]
	v_pk_add_f32 v[0:1], v[44:45], v[0:1]
	v_exp_f32_e32 v38, v232
	v_pk_add_f32 v[0:1], v[46:47], v[0:1]
	v_exp_f32_e32 v39, v233
	v_pk_add_f32 v[0:1], v[32:33], v[0:1]
	v_cvt_pk_bf16_f32 v16, v110, v111
	v_cvt_pk_bf16_f32 v17, v154, v155
	v_add_u32_e32 v154, 0x9000, v207
	v_pk_add_f32 v[0:1], v[34:35], v[0:1]
	v_cvt_pk_bf16_f32 v18, v160, v161
	v_cvt_pk_bf16_f32 v19, v164, v165
	v_add_u32_e32 v160, 0xd000, v207
	v_pk_add_f32 v[0:1], v[36:37], v[0:1]
	ds_read2_b64 v[20:23], v160 offset0:32 offset1:34
	v_pk_add_f32 v[0:1], v[38:39], v[0:1]
	s_nop 0
	v_add_f32_e32 v0, v0, v1
	v_mov_b32_e32 v142, v0
	v_mov_b32_e32 v143, v0
	s_nop 1
	v_permlane32_swap_b32_e32 v142, v143
	s_waitcnt lgkmcnt(0)
	v_add_f32_e32 v0, v142, v143
	v_sub_f32_e32 v1, v96, v213
	v_exp_f32_e32 v1, v1
	s_nop 0
	v_add_f32_e32 v96, v1, v0
	ds_read2_b64 v[0:3], v154 offset1:2
	v_cvt_pk_bf16_f32 v110, v102, v103
	v_cvt_pk_bf16_f32 v111, v112, v113
	v_cvt_pk_bf16_f32 v112, v156, v157
	v_cvt_pk_bf16_f32 v113, v162, v163
	ds_read2_b64 v[154:157], v154 offset0:4 offset1:6
	s_waitcnt lgkmcnt(1)
	v_mfma_f32_32x32x16_bf16 v[0:15], v[0:3], v[16:19], 0
	s_waitcnt lgkmcnt(0)
	v_mfma_f32_32x32x16_bf16 v[0:15], v[154:157], v[110:113], v[0:15]
	ds_read2_b64 v[154:157], v160 offset0:36 offset1:38
	v_mfma_f32_32x32x16_bf16 v[16:31], v[20:23], v[16:19], 0
	s_waitcnt lgkmcnt(0)
	v_mfma_f32_32x32x16_bf16 v[16:31], v[154:157], v[110:113], v[16:31]
	v_cvt_pk_bf16_f32 v110, v78, v79
	v_add_u32_e32 v78, 0x9000, v208
	v_cvt_pk_bf16_f32 v111, v106, v107
	v_cvt_pk_bf16_f32 v112, v118, v119
	v_cvt_pk_bf16_f32 v113, v158, v159
	ds_read2_b64 v[154:157], v78 offset1:2
	v_add_u32_e32 v106, 0xd000, v208
	s_waitcnt lgkmcnt(0)
	v_mfma_f32_32x32x16_bf16 v[0:15], v[154:157], v[110:113], v[0:15]
	ds_read2_b64 v[154:157], v106 offset0:32 offset1:34
	v_cvt_pk_bf16_f32 v102, v68, v69
	v_cvt_pk_bf16_f32 v103, v76, v77
	v_cvt_pk_bf16_f32 v104, v104, v105
	v_cvt_pk_bf16_f32 v105, v114, v115
	ds_read2_b64 v[76:79], v78 offset0:4 offset1:6
	s_waitcnt lgkmcnt(0)
	v_mfma_f32_32x32x16_bf16 v[0:15], v[76:79], v[102:105], v[0:15]
	ds_read2_b64 v[76:79], v106 offset0:36 offset1:38
	v_mfma_f32_32x32x16_bf16 v[16:31], v[154:157], v[110:113], v[16:31]
	s_waitcnt lgkmcnt(0)
	v_mfma_f32_32x32x16_bf16 v[16:31], v[76:79], v[102:105], v[16:31]
	v_cvt_pk_bf16_f32 v76, v64, v65
	v_add_u32_e32 v64, 0x9000, v209
	v_cvt_pk_bf16_f32 v77, v72, v73
	v_cvt_pk_bf16_f32 v78, v100, v101
	v_cvt_pk_bf16_f32 v79, v108, v109
	ds_read2_b64 v[100:103], v64 offset1:2
	v_add_u32_e32 v72, 0xd000, v209
	s_waitcnt lgkmcnt(0)
	v_mfma_f32_32x32x16_bf16 v[0:15], v[100:103], v[76:79], v[0:15]
	ds_read2_b64 v[100:103], v72 offset0:32 offset1:34
	v_cvt_pk_bf16_f32 v68, v58, v59
	v_cvt_pk_bf16_f32 v69, v62, v63
	v_cvt_pk_bf16_f32 v70, v70, v71
	v_cvt_pk_bf16_f32 v71, v98, v99
	ds_read2_b64 v[62:65], v64 offset0:4 offset1:6
	s_waitcnt lgkmcnt(0)
	v_mfma_f32_32x32x16_bf16 v[0:15], v[62:65], v[68:71], v[0:15]
	ds_read2_b64 v[62:65], v72 offset0:36 offset1:38
	v_cvt_pk_bf16_f32 v56, v56, v57
	v_cvt_pk_bf16_f32 v57, v60, v61
	v_cvt_pk_bf16_f32 v58, v66, v67
	v_cvt_pk_bf16_f32 v59, v74, v75
	v_mfma_f32_32x32x16_bf16 v[16:31], v[100:103], v[76:79], v[16:31]
	s_waitcnt lgkmcnt(0)
	v_mfma_f32_32x32x16_bf16 v[16:31], v[62:65], v[68:71], v[16:31]
	v_add_u32_e32 v64, 0x9000, v210
	ds_read2_b64 v[60:63], v64 offset1:2
	v_add_u32_e32 v65, 0xd000, v210
	s_waitcnt lgkmcnt(0)
	v_mfma_f32_32x32x16_bf16 v[0:15], v[60:63], v[56:59], v[0:15]
	ds_read2_b64 v[60:63], v65 offset0:32 offset1:34
	v_cvt_pk_bf16_f32 v48, v48, v49
	v_cvt_pk_bf16_f32 v49, v50, v51
	v_cvt_pk_bf16_f32 v50, v52, v53
	v_cvt_pk_bf16_f32 v51, v54, v55
	ds_read2_b64 v[52:55], v64 offset0:4 offset1:6
	s_waitcnt lgkmcnt(0)
	v_mfma_f32_32x32x16_bf16 v[0:15], v[52:55], v[48:51], v[0:15]
	ds_read2_b64 v[52:55], v65 offset0:36 offset1:38
	v_cvt_pk_bf16_f32 v40, v40, v41
	v_cvt_pk_bf16_f32 v41, v42, v43
	v_cvt_pk_bf16_f32 v42, v44, v45
	v_cvt_pk_bf16_f32 v43, v46, v47
	v_mfma_f32_32x32x16_bf16 v[16:31], v[60:63], v[56:59], v[16:31]
	s_waitcnt lgkmcnt(0)
	v_mfma_f32_32x32x16_bf16 v[16:31], v[52:55], v[48:51], v[16:31]
	v_add_u32_e32 v48, 0x9000, v211
	ds_read2_b64 v[44:47], v48 offset1:2
	v_add_u32_e32 v49, 0xd000, v211
	s_waitcnt lgkmcnt(0)
	v_mfma_f32_32x32x16_bf16 v[0:15], v[44:47], v[40:43], v[0:15]
	ds_read2_b64 v[44:47], v49 offset0:32 offset1:34
	v_cvt_pk_bf16_f32 v32, v32, v33
	v_cvt_pk_bf16_f32 v33, v34, v35
	v_cvt_pk_bf16_f32 v34, v36, v37
	v_cvt_pk_bf16_f32 v35, v38, v39
	ds_read2_b64 v[36:39], v48 offset0:4 offset1:6
	s_waitcnt lgkmcnt(0)
	v_mfma_f32_32x32x16_bf16 v[0:15], v[36:39], v[32:35], v[0:15]
	ds_read2_b64 v[36:39], v49 offset0:36 offset1:38
	v_mfma_f32_32x32x16_bf16 v[16:31], v[44:47], v[40:43], v[16:31]
	s_waitcnt lgkmcnt(0)
	v_mfma_f32_32x32x16_bf16 v[16:31], v[36:39], v[32:35], v[16:31]
	v_div_scale_f32 v32, s[68:69], v96, v96, 1.0
	v_rcp_f32_e32 v33, v32
	s_nop 0
	v_fma_f32 v34, -v32, v33, 1.0
	v_fmac_f32_e32 v33, v34, v33
	v_div_scale_f32 v34, vcc, 1.0, v96, 1.0
	v_mul_f32_e32 v35, v34, v33
	v_fma_f32 v36, -v32, v35, v34
	v_fmac_f32_e32 v35, v36, v33
	v_fma_f32 v32, -v32, v35, v34
	v_div_fmas_f32 v32, v32, v33, v35
	v_div_fixup_f32 v34, v32, v96, 1.0
	v_mul_f32_e32 v0, v0, v34
	v_mul_f32_e32 v1, v1, v34
	v_cvt_pk_bf16_f32 v0, v0, v1
	v_mul_f32_e32 v1, v2, v34
	v_mad_i64_i32 v[32:33], s[68:69], v153, s65, v[116:117]
	v_and_b32_e32 v36, 63, v251
	v_and_b32_e32 v35, 31, v251
	v_lshrrev_b32_e32 v37, 5, v36
	v_lshlrev_b32_e32 v37, 3, v37
	s_movk_i32 s58, 0x90
	v_mad_u32_u24 v35, v35, s58, v37
	s_movk_i32 s59, 0x1200
	v_mad_u32_u24 v35, v254, s59, v35
	v_add_u32_e32 v35, 0x12000, v35
	v_lshrrev_b32_e32 v37, 3, v36
	v_and_b32_e32 v40, 7, v36
	v_lshlrev_b32_e32 v40, 4, v40
	v_mad_u32_u24 v36, v37, s58, v40
	v_mad_u32_u24 v36, v254, s59, v36
	v_add_u32_e32 v36, 0x12000, v36
	s_movk_i32 s58, 0xc00
	v_mad_u32_u24 v37, v37, s58, v40
	v_readfirstlane_b32 s56, v32
	v_readfirstlane_b32 s57, v33
	v_mul_f32_e32 v2, v3, v34
	v_cvt_pk_bf16_f32 v1, v1, v2
	ds_write_b64 v35, v[0:1]
	v_mul_f32_e32 v0, v4, v34
	v_mul_f32_e32 v1, v5, v34
	v_cvt_pk_bf16_f32 v0, v0, v1
	v_mul_f32_e32 v1, v6, v34
	v_mul_f32_e32 v2, v7, v34
	v_cvt_pk_bf16_f32 v1, v1, v2
	ds_write_b64 v35, v[0:1] offset:16
	v_mul_f32_e32 v0, v8, v34
	v_mul_f32_e32 v1, v9, v34
	v_cvt_pk_bf16_f32 v0, v0, v1
	v_mul_f32_e32 v1, v10, v34
	v_mul_f32_e32 v2, v11, v34
	v_cvt_pk_bf16_f32 v1, v1, v2
	ds_write_b64 v35, v[0:1] offset:32
	v_mul_f32_e32 v0, v12, v34
	v_mul_f32_e32 v1, v13, v34
	v_cvt_pk_bf16_f32 v0, v0, v1
	v_mul_f32_e32 v1, v14, v34
	v_mul_f32_e32 v2, v15, v34
	v_cvt_pk_bf16_f32 v1, v1, v2
	ds_write_b64 v35, v[0:1] offset:48
	v_mul_f32_e32 v0, v16, v34
	v_mul_f32_e32 v1, v17, v34
	v_cvt_pk_bf16_f32 v0, v0, v1
	v_mul_f32_e32 v1, v18, v34
	v_mul_f32_e32 v2, v19, v34
	v_cvt_pk_bf16_f32 v1, v1, v2
	ds_write_b64 v35, v[0:1] offset:64
	v_mul_f32_e32 v0, v20, v34
	v_mul_f32_e32 v1, v21, v34
	v_cvt_pk_bf16_f32 v0, v0, v1
	v_mul_f32_e32 v1, v22, v34
	v_mul_f32_e32 v2, v23, v34
	v_cvt_pk_bf16_f32 v1, v1, v2
	ds_write_b64 v35, v[0:1] offset:80
	v_mul_f32_e32 v0, v24, v34
	v_mul_f32_e32 v1, v25, v34
	v_cvt_pk_bf16_f32 v0, v0, v1
	v_mul_f32_e32 v1, v26, v34
	v_mul_f32_e32 v2, v27, v34
	v_cvt_pk_bf16_f32 v1, v1, v2
	ds_write_b64 v35, v[0:1] offset:96
	v_mul_f32_e32 v0, v28, v34
	v_mul_f32_e32 v1, v29, v34
	v_cvt_pk_bf16_f32 v0, v0, v1
	v_mul_f32_e32 v1, v30, v34
	s_andn2_b64 vcc, exec, s[76:77]
	v_mul_f32_e32 v2, v31, v34
	v_cvt_pk_bf16_f32 v1, v1, v2
	ds_write_b64 v35, v[0:1] offset:112
	s_waitcnt lgkmcnt(0)
	ds_read_b128 v[0:3], v36
	ds_read_b128 v[4:7], v36 offset:1152
	ds_read_b128 v[8:11], v36 offset:2304
	ds_read_b128 v[12:15], v36 offset:3456
	s_waitcnt lgkmcnt(3)
	global_store_dwordx4 v37, v[0:3], s[56:57]
	s_add_u32 s56, s56, 0x6000
	s_addc_u32 s57, s57, 0
	s_waitcnt lgkmcnt(2)
	global_store_dwordx4 v37, v[4:7], s[56:57]
	s_add_u32 s56, s56, 0x6000
	s_addc_u32 s57, s57, 0
	s_waitcnt lgkmcnt(1)
	global_store_dwordx4 v37, v[8:11], s[56:57]
	s_add_u32 s56, s56, 0x6000
	s_addc_u32 s57, s57, 0
	s_waitcnt lgkmcnt(0)
	global_store_dwordx4 v37, v[12:15], s[56:57]
	s_nop 1
	s_setprio 0
	s_cbranch_vccz .Lattn_exit

.Lattn_prio_skip:
	ds_read_b128 v[20:23], v243 offset:144
	ds_read_b128 v[16:19], v243 offset:16
	v_or_b32_e32 v153, s68, v184
	v_or_b32_e32 v98, s91, v153
	v_lshlrev_b32_e32 v96, 5, v98
	v_or_b32_e32 v24, v96, v126
	v_lshlrev_b32_e32 v54, 2, v24
	ds_read_b128 v[42:45], v243 offset:128
	ds_read_b128 v[24:27], v252 offset:4096
	ds_read_b128 v[28:31], v252 offset:22144
	ds_read_b128 v[46:49], v243
	ds_read_b128 v[50:53], v252
	s_nop 0
	ds_read_b128 v[54:57], v252 offset:16384
	s_lshl_b32 s55, s97, 2
	v_lshlrev_b32_e32 v34, 16, v15
	v_and_b32_e32 v32, 0xffff0000, v15
	v_lshlrev_b32_e32 v39, 16, v9
	v_and_b32_e32 v15, 0xffff0000, v9
	v_lshlrev_b32_e32 v41, 16, v8
	v_lshlrev_b32_e32 v40, 16, v12
	v_and_b32_e32 v9, 0xffff0000, v8
	v_and_b32_e32 v8, 0xffff0000, v12
	v_lshlrev_b32_e32 v12, 16, v7
	v_and_b32_e32 v58, 0xffff0000, v7
	v_lshlrev_b32_e32 v7, 16, v1
	v_and_b32_e32 v63, 0xffff0000, v1
	v_lshlrev_b32_e32 v65, 16, v0
	v_lshlrev_b32_e32 v64, 16, v4
	v_and_b32_e32 v1, 0xffff0000, v0
	v_and_b32_e32 v0, 0xffff0000, v4
	v_lshlrev_b32_e32 v35, 16, v11
	v_and_b32_e32 v33, 0xffff0000, v11
	v_lshlrev_b32_e32 v36, 16, v14
	v_lshlrev_b32_e32 v37, 16, v10
	v_and_b32_e32 v11, 0xffff0000, v10
	v_and_b32_e32 v10, 0xffff0000, v14
	v_lshlrev_b32_e32 v38, 16, v13
	v_and_b32_e32 v14, 0xffff0000, v13
	v_lshlrev_b32_e32 v13, 16, v3
	v_and_b32_e32 v59, 0xffff0000, v3
	v_lshlrev_b32_e32 v61, 16, v2
	v_lshlrev_b32_e32 v60, 16, v6
	v_and_b32_e32 v3, 0xffff0000, v2
	v_and_b32_e32 v2, 0xffff0000, v6
	v_lshlrev_b32_e32 v6, 16, v5
	v_mov_b32_e32 v99, s55
	v_pk_mul_f32 v[156:157], v[64:65], v[64:65]
	v_pk_mul_f32 v[158:159], v[0:1], v[0:1]
	v_and_b32_e32 v62, 0xffff0000, v5
	v_pk_mul_f32 v[118:119], v[6:7], v[6:7]
	v_mov_b32_e32 v214, v253
	v_add_f32_e32 v99, v157, v159
	v_pk_mul_f32 v[154:155], v[62:63], v[62:63]
	v_add_f32_e32 v99, v119, v99
	v_pk_mul_f32 v[78:79], v[60:61], v[60:61]
	v_add_f32_e32 v99, v155, v99
	v_pk_mul_f32 v[116:117], v[2:3], v[2:3]
	v_add_f32_e32 v79, v79, v99
	v_pk_mul_f32 v[74:75], v[12:13], v[12:13]
	v_add_f32_e32 v79, v117, v79
	v_pk_mul_f32 v[76:77], v[58:59], v[58:59]
	v_add_f32_e32 v75, v75, v79
	v_pk_mul_f32 v[70:71], v[40:41], v[40:41]
	v_add_f32_e32 v75, v77, v75
	v_pk_mul_f32 v[72:73], v[8:9], v[8:9]
	v_add_f32_e32 v71, v71, v75
	v_add_f32_e32 v71, v73, v71
	v_fmac_f32_e32 v71, v39, v39
	v_fmac_f32_e32 v71, v15, v15
	v_fmac_f32_e32 v71, v37, v37
	v_fmac_f32_e32 v71, v11, v11
	v_fmac_f32_e32 v71, v35, v35
	v_fmac_f32_e32 v71, v33, v33
	v_mov_b32_e32 v68, v14
	v_mov_b32_e32 v69, v38
	v_pk_mul_f32 v[68:69], v[68:69], v[68:69]
	v_mov_b32_e32 v66, v10
	v_mov_b32_e32 v67, v36
	v_pk_mul_f32 v[66:67], v[66:67], v[66:67]
	v_mov_b32_e32 v4, v32
	v_mov_b32_e32 v5, v34
	v_pk_mul_f32 v[4:5], v[4:5], v[4:5]
	s_waitcnt lgkmcnt(0)
	v_mov_b32_e32 v162, v20
	s_waitcnt lgkmcnt(0)
	v_mov_b32_e32 v163, v16
	v_add_f32_e32 v16, v156, v71
	v_add_f32_e32 v16, v158, v16
	v_add_f32_e32 v16, v118, v16
	v_add_f32_e32 v16, v154, v16
	v_add_f32_e32 v16, v78, v16
	v_add_f32_e32 v16, v116, v16
	v_add_f32_e32 v16, v74, v16
	v_add_f32_e32 v16, v76, v16
	v_add_f32_e32 v16, v70, v16
	v_add_f32_e32 v16, v72, v16
	v_add_f32_e32 v16, v69, v16
	v_add_f32_e32 v16, v68, v16
	v_add_f32_e32 v16, v67, v16
	v_add_f32_e32 v16, v66, v16
	v_add_f32_e32 v5, v5, v16
	v_add_f32_e32 v16, v4, v5
	v_mov_b32_e32 v161, v18
	v_mov_b32_e32 v142, v16
	v_mov_b32_e32 v143, v16
	s_nop 1
	v_permlane32_swap_b32_e32 v142, v143
	s_waitcnt lgkmcnt(0)
	v_mov_b32_e32 v66, v42
	s_waitcnt lgkmcnt(0)
	v_mov_b32_e32 v67, v46
	v_mov_b32_e32 v46, v43
	v_mov_b32_e32 v68, v50
	s_waitcnt lgkmcnt(0)
	v_add_f32_e32 v16, v142, v143
	v_fmamk_f32 v16, v16, 0x3c800000, v189
	v_rsq_f32_e32 v16, v16
	v_mov_b32_e32 v69, v54
	v_mov_b32_e32 v164, v44
	v_mov_b32_e32 v165, v48
	v_mul_f32_e32 v70, 0x3e38aa3b, v16
	v_pk_mul_f32 v[64:65], v[70:71], v[64:65] op_sel_hi:[0,1]
	v_pk_mul_f32 v[0:1], v[70:71], v[0:1] op_sel_hi:[0,1]
	v_pk_mul_f32 v[64:65], v[66:67], v[64:65]
	v_mov_b32_e32 v66, v54
	v_mov_b32_e32 v67, v50
	v_pk_mul_f32 v[0:1], v[46:47], v[0:1]
	v_mov_b32_e32 v50, v55
	v_mov_b32_e32 v54, v51
	v_pk_mul_f32 v[42:43], v[50:51], v[0:1]
	v_pk_mul_f32 v[0:1], v[54:55], v[0:1]
	v_sub_f32_e32 v42, v43, v42
	v_add_f32_e32 v43, v0, v1
	v_pk_mul_f32 v[0:1], v[70:71], v[6:7] op_sel_hi:[0,1]
	v_mov_b32_e32 v4, v52
	v_mov_b32_e32 v5, v56
	v_pk_mul_f32 v[0:1], v[0:1], v[164:165]
	v_mov_b32_e32 v6, v56
	v_mov_b32_e32 v7, v52
	v_pk_mul_f32 v[6:7], v[0:1], v[6:7]
	v_pk_mul_f32 v[0:1], v[0:1], v[4:5]
	v_sub_f32_e32 v6, v7, v6
	v_add_f32_e32 v7, v0, v1
	v_pk_mul_f32 v[0:1], v[70:71], v[62:63] op_sel_hi:[0,1]
	v_mov_b32_e32 v48, v45
	v_pk_mul_f32 v[0:1], v[0:1], v[48:49]
	v_mov_b32_e32 v52, v57
	v_mov_b32_e32 v56, v53
	v_pk_mul_f32 v[4:5], v[0:1], v[52:53]
	v_pk_mul_f32 v[0:1], v[0:1], v[56:57]
	v_mov_b32_e32 v168, v24
	v_add_f32_e32 v45, v0, v1
	v_pk_mul_f32 v[0:1], v[70:71], v[60:61] op_sel_hi:[0,1]
	v_mov_b32_e32 v169, v28
	v_sub_f32_e32 v44, v5, v4
	v_pk_mul_f32 v[0:1], v[0:1], v[162:163]
	v_mov_b32_e32 v4, v28
	v_mov_b32_e32 v5, v24
	v_pk_mul_f32 v[4:5], v[0:1], v[4:5]
	v_pk_mul_f32 v[0:1], v[0:1], v[168:169]
	v_sub_f32_e32 v4, v5, v4
	v_add_f32_e32 v5, v0, v1
	v_pk_mul_f32 v[0:1], v[70:71], v[2:3] op_sel_hi:[0,1]
	v_mov_b32_e32 v16, v21
	v_pk_mul_f32 v[0:1], v[0:1], v[16:17]
	v_mov_b32_e32 v24, v29
	v_mov_b32_e32 v28, v25
	v_pk_mul_f32 v[2:3], v[0:1], v[24:25]
	v_pk_mul_f32 v[0:1], v[0:1], v[28:29]
	v_mov_b32_e32 v160, v22
	v_add_f32_e32 v17, v0, v1
	v_pk_mul_f32 v[0:1], v[70:71], v[12:13] op_sel_hi:[0,1]
	v_mov_b32_e32 v166, v26
	v_mov_b32_e32 v167, v30
	v_sub_f32_e32 v16, v3, v2
	v_pk_mul_f32 v[0:1], v[0:1], v[160:161]
	v_mov_b32_e32 v2, v30
	v_mov_b32_e32 v3, v26
	v_pk_mul_f32 v[2:3], v[0:1], v[2:3]
	v_pk_mul_f32 v[0:1], v[0:1], v[166:167]
	v_mov_b32_e32 v18, v23
	v_add_f32_e32 v13, v0, v1
	v_pk_mul_f32 v[0:1], v[70:71], v[58:59] op_sel_hi:[0,1]
	v_pk_mul_f32 v[0:1], v[0:1], v[18:19]
	v_mov_b32_e32 v26, v31
	v_mov_b32_e32 v30, v27
	v_sub_f32_e32 v12, v3, v2
	v_pk_mul_f32 v[2:3], v[0:1], v[26:27]
	v_pk_mul_f32 v[0:1], v[0:1], v[30:31]
	v_pk_mul_f32 v[66:67], v[66:67], v[64:65]
	v_pk_mul_f32 v[64:65], v[68:69], v[64:65]
	v_sub_f32_e32 v2, v3, v2
	v_add_f32_e32 v0, v0, v1
	v_sub_f32_e32 v20, v67, v66
	v_add_f32_e32 v22, v64, v65
	v_cvt_pk_bf16_f32 v48, v20, v42
	v_cvt_pk_bf16_f32 v49, v6, v44
	v_cvt_pk_bf16_f32 v50, v4, v16
	v_cvt_pk_bf16_f32 v51, v12, v2
	v_cvt_pk_bf16_f32 v116, v22, v43
	v_cvt_pk_bf16_f32 v117, v7, v45
	v_cvt_pk_bf16_f32 v118, v5, v17
	v_cvt_pk_bf16_f32 v119, v13, v0
	ds_read_b128 v[0:3], v243 offset:192
	ds_read_b128 v[4:7], v243 offset:64
	v_or_b32_e32 v96, v96, v127
	v_lshlrev_b32_e32 v12, 2, v96
	ds_read_b128 v[16:19], v252 offset:26240
	ds_read_b128 v[20:23], v252 offset:8192
	ds_read_b128 v[24:27], v243 offset:208
	ds_read_b128 v[28:31], v243 offset:80
	ds_read_b128 v[42:45], v252 offset:30336
	ds_read_b128 v[52:55], v252 offset:12288
	v_pk_mul_f32 v[12:13], v[70:71], v[40:41] op_sel_hi:[0,1]
	v_pk_mul_f32 v[8:9], v[70:71], v[8:9] op_sel_hi:[0,1]
	s_lshl_b32 s69, s97, 6
	s_cmp_eq_u32 s88, 0
	s_cselect_b64 s[78:79], -1, 0
	s_cmp_lg_u32 s88, 0
	s_waitcnt lgkmcnt(0)
	v_mov_b32_e32 v40, v0
	s_waitcnt lgkmcnt(0)
	v_mov_b32_e32 v41, v4
	v_pk_mul_f32 v[12:13], v[12:13], v[40:41]
	v_mov_b32_e32 v40, v16
	v_mov_b32_e32 v41, v20
	v_pk_mul_f32 v[40:41], v[12:13], v[40:41]
	v_mov_b32_e32 v4, v1
	v_sub_f32_e32 v46, v41, v40
	v_mov_b32_e32 v40, v20
	v_mov_b32_e32 v41, v16
	v_pk_mul_f32 v[0:1], v[8:9], v[4:5]
	v_mov_b32_e32 v20, v17
	v_mov_b32_e32 v16, v21
	v_pk_mul_f32 v[4:5], v[0:1], v[20:21]
	v_pk_mul_f32 v[0:1], v[0:1], v[16:17]
	v_sub_f32_e32 v8, v5, v4
	v_add_f32_e32 v9, v0, v1
	v_pk_mul_f32 v[0:1], v[70:71], v[38:39] op_sel_hi:[0,1]
	v_mov_b32_e32 v4, v2
	v_mov_b32_e32 v5, v6
	v_pk_mul_f32 v[0:1], v[0:1], v[4:5]
	v_mov_b32_e32 v4, v18
	v_mov_b32_e32 v5, v22
	v_pk_mul_f32 v[12:13], v[12:13], v[40:41]
	v_pk_mul_f32 v[4:5], v[0:1], v[4:5]
	v_add_f32_e32 v12, v12, v13
	v_sub_f32_e32 v13, v5, v4
	v_mov_b32_e32 v4, v22
	v_mov_b32_e32 v5, v18
	v_pk_mul_f32 v[0:1], v[0:1], v[4:5]
	v_mov_b32_e32 v6, v3
	v_add_f32_e32 v4, v0, v1
	v_pk_mul_f32 v[0:1], v[70:71], v[14:15] op_sel_hi:[0,1]
	v_pk_mul_f32 v[0:1], v[0:1], v[6:7]
	v_mov_b32_e32 v22, v19
	v_mov_b32_e32 v18, v23
	v_pk_mul_f32 v[2:3], v[0:1], v[22:23]
	v_pk_mul_f32 v[0:1], v[0:1], v[18:19]
	v_sub_f32_e32 v5, v3, v2
	v_add_f32_e32 v6, v0, v1
	v_pk_mul_f32 v[0:1], v[70:71], v[36:37] op_sel_hi:[0,1]
	s_waitcnt lgkmcnt(0)
	v_mov_b32_e32 v2, v24
	s_waitcnt lgkmcnt(0)
	v_mov_b32_e32 v3, v28
	v_pk_mul_f32 v[0:1], v[0:1], v[2:3]
	v_mov_b32_e32 v2, v42
	v_mov_b32_e32 v3, v52
	v_pk_mul_f32 v[2:3], v[0:1], v[2:3]
	v_mov_b32_e32 v28, v25
	v_sub_f32_e32 v7, v3, v2
	v_mov_b32_e32 v2, v52
	v_mov_b32_e32 v3, v42
	v_pk_mul_f32 v[0:1], v[0:1], v[2:3]
	v_mov_b32_e32 v52, v43
	v_add_f32_e32 v14, v0, v1
	v_pk_mul_f32 v[0:1], v[70:71], v[10:11] op_sel_hi:[0,1]
	v_pk_mul_f32 v[0:1], v[0:1], v[28:29]
	v_mov_b32_e32 v42, v53
	v_pk_mul_f32 v[2:3], v[0:1], v[52:53]
	v_pk_mul_f32 v[0:1], v[0:1], v[42:43]
	v_sub_f32_e32 v10, v3, v2
	v_add_f32_e32 v11, v0, v1
	v_pk_mul_f32 v[0:1], v[70:71], v[34:35] op_sel_hi:[0,1]
	v_mov_b32_e32 v2, v26
	v_mov_b32_e32 v3, v30
	v_pk_mul_f32 v[0:1], v[0:1], v[2:3]
	v_mov_b32_e32 v2, v44
	v_mov_b32_e32 v3, v54
	v_pk_mul_f32 v[2:3], v[0:1], v[2:3]
	v_mov_b32_e32 v30, v27
	v_sub_f32_e32 v15, v3, v2
	v_mov_b32_e32 v2, v54
	v_mov_b32_e32 v3, v44
	v_pk_mul_f32 v[0:1], v[0:1], v[2:3]
	v_mov_b32_e32 v54, v45
	v_add_f32_e32 v16, v0, v1
	v_pk_mul_f32 v[0:1], v[70:71], v[32:33] op_sel_hi:[0,1]
	v_pk_mul_f32 v[0:1], v[0:1], v[30:31]
	v_mov_b32_e32 v44, v55
	v_pk_mul_f32 v[2:3], v[0:1], v[54:55]
	v_pk_mul_f32 v[0:1], v[0:1], v[44:45]
	v_sub_f32_e32 v2, v3, v2
	v_add_f32_e32 v0, v0, v1
	v_cvt_pk_bf16_f32 v154, v46, v8
	v_cvt_pk_bf16_f32 v155, v13, v5
	v_cvt_pk_bf16_f32 v156, v7, v10
	v_cvt_pk_bf16_f32 v157, v15, v2
	v_cvt_pk_bf16_f32 v158, v12, v9
	v_cvt_pk_bf16_f32 v159, v4, v6
	v_cvt_pk_bf16_f32 v160, v14, v11
	v_cvt_pk_bf16_f32 v161, v16, v0
	s_barrier
	ds_read_b128 v[0:3], v192
	ds_read_b128 v[52:55], v195 offset:32
	s_waitcnt lgkmcnt(1)
	v_mfma_f32_32x32x16_bf16 v[64:79], v[0:3], v[48:51], 0
	ds_read_b128 v[0:3], v192 offset:32
	ds_read_b128 v[162:165], v196 offset:32
	s_waitcnt lgkmcnt(1)
	v_mfma_f32_32x32x16_bf16 v[64:79], v[0:3], v[154:157], v[64:79]
	ds_read_b128 v[0:3], v192 offset:64
	s_waitcnt lgkmcnt(0)
	v_mfma_f32_32x32x16_bf16 v[64:79], v[0:3], v[116:119], v[64:79]
	ds_read_b128 v[0:3], v192 offset:96
	s_waitcnt lgkmcnt(0)
	v_mfma_f32_32x32x16_bf16 v[64:79], v[0:3], v[158:161], v[64:79]
	ds_read_b128 v[0:3], v193
	s_waitcnt lgkmcnt(0)
	v_mfma_f32_32x32x16_bf16 v[32:47], v[0:3], v[48:51], 0
	ds_read_b128 v[0:3], v193 offset:32
	s_waitcnt lgkmcnt(0)
	v_mfma_f32_32x32x16_bf16 v[32:47], v[0:3], v[154:157], v[32:47]
	ds_read_b128 v[0:3], v193 offset:64
	s_waitcnt lgkmcnt(0)
	v_mfma_f32_32x32x16_bf16 v[32:47], v[0:3], v[116:119], v[32:47]
	ds_read_b128 v[0:3], v193 offset:96
	s_waitcnt lgkmcnt(0)
	v_mfma_f32_32x32x16_bf16 v[32:47], v[0:3], v[158:161], v[32:47]
	ds_read_b128 v[0:3], v194
	s_waitcnt lgkmcnt(0)
	v_mfma_f32_32x32x16_bf16 v[16:31], v[0:3], v[48:51], 0
	ds_read_b128 v[0:3], v194 offset:32
	s_waitcnt lgkmcnt(0)
	v_mfma_f32_32x32x16_bf16 v[16:31], v[0:3], v[154:157], v[16:31]
	ds_read_b128 v[0:3], v194 offset:64
	s_waitcnt lgkmcnt(0)
	v_mfma_f32_32x32x16_bf16 v[16:31], v[0:3], v[116:119], v[16:31]
	ds_read_b128 v[0:3], v194 offset:96
	s_waitcnt lgkmcnt(0)
	v_mfma_f32_32x32x16_bf16 v[16:31], v[0:3], v[158:161], v[16:31]
	ds_read_b128 v[0:3], v195
	s_waitcnt lgkmcnt(0)
	v_mfma_f32_32x32x16_bf16 v[0:15], v[0:3], v[48:51], 0
	v_mfma_f32_32x32x16_bf16 v[0:15], v[52:55], v[154:157], v[0:15]
	ds_read_b128 v[52:55], v195 offset:64
	s_waitcnt lgkmcnt(0)
	v_mfma_f32_32x32x16_bf16 v[0:15], v[52:55], v[116:119], v[0:15]
	ds_read_b128 v[52:55], v195 offset:96
	s_waitcnt lgkmcnt(0)
	v_mfma_f32_32x32x16_bf16 v[0:15], v[52:55], v[158:161], v[0:15]
	ds_read_b128 v[52:55], v196
	s_waitcnt lgkmcnt(0)
	v_mfma_f32_32x32x16_bf16 v[48:63], v[52:55], v[48:51], 0
	v_mfma_f32_32x32x16_bf16 v[48:63], v[162:165], v[154:157], v[48:63]
	ds_read_b128 v[154:157], v196 offset:64
	s_waitcnt lgkmcnt(0)
	v_mfma_f32_32x32x16_bf16 v[48:63], v[154:157], v[116:119], v[48:63]
	ds_read_b128 v[116:119], v196 offset:96
	s_waitcnt lgkmcnt(0)
	v_mfma_f32_32x32x16_bf16 v[48:63], v[116:119], v[158:161], v[48:63]
	s_cbranch_scc0 .LBB0_356
	v_cndmask_b32_e64 v158, v212, v64, s[2:3]
	v_cndmask_b32_e64 v157, v65, v212, s[4:5]
	v_cndmask_b32_e64 v156, v212, v66, s[6:7]
	v_cndmask_b32_e64 v155, v212, v67, s[8:9]
	v_cndmask_b32_e64 v154, v212, v68, s[10:11]
	v_cndmask_b32_e64 v119, v212, v69, s[12:13]
	v_cndmask_b32_e64 v118, v212, v70, s[14:15]
	v_cndmask_b32_e64 v99, v212, v71, s[16:17]
	v_cndmask_b32_e64 v71, v212, v72, s[18:19]
	v_cndmask_b32_e64 v70, v212, v73, s[20:21]
	v_cndmask_b32_e64 v69, v212, v74, s[22:23]
	v_cndmask_b32_e64 v68, v212, v75, s[24:25]
	v_cndmask_b32_e64 v67, v212, v76, s[26:27]
	v_cndmask_b32_e64 v66, v212, v77, s[28:29]
	v_cndmask_b32_e64 v65, v212, v78, s[30:31]
	v_cndmask_b32_e64 v64, v212, v79, s[34:35]
	s_branch .LBB0_357

.LBB0_357:
	s_mov_b32 s64, 0xff800000
	v_cndmask_b32_e64 v72, v48, v212, s[2:3]
	v_cndmask_b32_e64 v216, v72, v48, s[4:5]
	v_max3_f32 v48, v158, s64, v157
	v_max3_f32 v48, v48, v156, v155
	v_max3_f32 v48, v48, v154, v119
	v_max3_f32 v48, v48, v118, v99
	v_max3_f32 v48, v48, v71, v70
	v_max3_f32 v48, v48, v69, v68
	v_max3_f32 v48, v48, v67, v66
	v_max3_f32 v48, v48, v65, v64
	v_max3_f32 v48, v48, v32, v33
	v_max3_f32 v48, v48, v34, v35
	v_max3_f32 v48, v48, v36, v37
	v_max3_f32 v48, v48, v38, v39
	v_max3_f32 v48, v48, v40, v41
	v_max3_f32 v48, v48, v42, v43
	v_max3_f32 v48, v48, v44, v45
	v_max3_f32 v48, v48, v46, v47
	v_max3_f32 v48, v48, v16, v17
	v_max3_f32 v48, v48, v18, v19
	v_max3_f32 v48, v48, v20, v21
	v_max3_f32 v48, v48, v22, v23
	v_max3_f32 v48, v48, v24, v25
	v_max3_f32 v48, v48, v26, v27
	v_max3_f32 v48, v48, v28, v29
	v_max3_f32 v48, v48, v30, v31
	v_max3_f32 v48, v48, v0, v1
	v_max3_f32 v48, v48, v2, v3
	v_max3_f32 v48, v48, v4, v5
	v_max3_f32 v48, v48, v6, v7
	v_max3_f32 v48, v48, v8, v9
	v_max3_f32 v48, v48, v10, v11
	v_max3_f32 v48, v48, v12, v13
	v_cndmask_b32_e64 v215, v212, v49, s[4:5]
	v_max3_f32 v48, v48, v14, v15
	v_cndmask_b32_e64 v217, v50, v212, s[6:7]
	v_cndmask_b32_e64 v218, v51, v212, s[8:9]
	v_max3_f32 v48, v48, v216, v215
	v_cndmask_b32_e64 v219, v52, v212, s[10:11]
	v_cndmask_b32_e64 v220, v53, v212, s[12:13]
	v_max3_f32 v48, v48, v217, v218
	v_cndmask_b32_e64 v221, v54, v212, s[14:15]
	v_cndmask_b32_e64 v222, v55, v212, s[16:17]
	v_max3_f32 v48, v48, v219, v220
	v_cndmask_b32_e64 v223, v56, v212, s[18:19]
	v_cndmask_b32_e64 v224, v57, v212, s[20:21]
	v_max3_f32 v48, v48, v221, v222
	v_cndmask_b32_e64 v225, v58, v212, s[22:23]
	v_cndmask_b32_e64 v226, v59, v212, s[24:25]
	v_max3_f32 v48, v48, v223, v224
	v_cndmask_b32_e64 v227, v60, v212, s[26:27]
	v_cndmask_b32_e64 v228, v61, v212, s[28:29]
	v_max3_f32 v48, v48, v225, v226
	v_cndmask_b32_e64 v229, v62, v212, s[30:31]
	v_cndmask_b32_e64 v230, v63, v212, s[34:35]
	v_max3_f32 v48, v48, v227, v228
	v_max3_f32 v48, v48, v229, v230
	v_mov_b32_e32 v142, v48
	v_mov_b32_e32 v143, v48
	s_nop 1
	v_permlane32_swap_b32_e32 v142, v143
	v_mul_f32_e32 v96, 0x3fb8aa3b, v214
	v_or_b32_e32 v213, s89, v98
	s_mov_b32 s55, 0x3fb8aa3b
	s_lshl_b32 s94, s69, 1
	s_waitcnt lgkmcnt(0)
	v_max3_f32 v231, v142, v143, v96
	v_sub_f32_e32 v50, v156, v231
	v_exp_f32_e32 v170, v50
	v_sub_f32_e32 v50, v155, v231
	v_exp_f32_e32 v171, v50
	v_sub_f32_e32 v50, v154, v231
	v_exp_f32_e32 v176, v50
	v_sub_f32_e32 v50, v119, v231
	v_exp_f32_e32 v177, v50
	v_sub_f32_e32 v50, v118, v231
	v_sub_f32_e32 v48, v158, v231
	v_exp_f32_e32 v180, v50
	v_sub_f32_e32 v50, v99, v231
	v_exp_f32_e32 v162, v48
	v_sub_f32_e32 v48, v157, v231
	v_exp_f32_e32 v181, v50
	v_sub_f32_e32 v50, v71, v231
	v_exp_f32_e32 v163, v48
	v_exp_f32_e32 v154, v50
	v_sub_f32_e32 v50, v70, v231
	v_exp_f32_e32 v155, v50
	v_pk_add_f32 v[232:233], v[68:69], v[230:231] op_sel:[0,1] op_sel_hi:[1,1] neg_lo:[0,1] neg_hi:[0,1]
	v_pk_add_f32 v[234:235], v[34:35], v[230:231] op_sel:[0,1] op_sel_hi:[1,1] neg_lo:[0,1] neg_hi:[0,1]
	v_exp_f32_e32 v164, v233
	v_exp_f32_e32 v158, v234
	v_exp_f32_e32 v165, v232
	v_pk_add_f32 v[232:233], v[66:67], v[230:231] op_sel:[0,1] op_sel_hi:[1,1] neg_lo:[0,1] neg_hi:[0,1]
	v_exp_f32_e32 v159, v235
	v_pk_add_f32 v[234:235], v[36:37], v[230:231] op_sel:[0,1] op_sel_hi:[1,1] neg_lo:[0,1] neg_hi:[0,1]
	v_pk_add_f32 v[48:49], v[162:163], 0 op_sel_hi:[1,0]
	v_exp_f32_e32 v172, v233
	v_exp_f32_e32 v166, v234
	v_pk_add_f32 v[48:49], v[170:171], v[48:49]
	v_exp_f32_e32 v173, v232
	v_pk_add_f32 v[232:233], v[64:65], v[230:231] op_sel:[0,1] op_sel_hi:[1,1] neg_lo:[0,1] neg_hi:[0,1]
	v_exp_f32_e32 v167, v235
	v_pk_add_f32 v[234:235], v[38:39], v[230:231] op_sel:[0,1] op_sel_hi:[1,1] neg_lo:[0,1] neg_hi:[0,1]
	v_pk_add_f32 v[48:49], v[176:177], v[48:49]
	v_exp_f32_e32 v178, v233
	v_pk_add_f32 v[236:237], v[32:33], v[230:231] op_sel:[0,1] op_sel_hi:[1,1] neg_lo:[0,1] neg_hi:[0,1]
	v_exp_f32_e32 v174, v234
	v_pk_add_f32 v[48:49], v[180:181], v[48:49]
	v_exp_f32_e32 v179, v232
	v_exp_f32_e32 v78, v236
	v_exp_f32_e32 v175, v235
	v_pk_add_f32 v[232:233], v[40:41], v[230:231] op_sel:[0,1] op_sel_hi:[1,1] neg_lo:[0,1] neg_hi:[0,1]
	v_pk_add_f32 v[48:49], v[154:155], v[48:49]
	v_exp_f32_e32 v79, v237
	v_exp_f32_e32 v70, v232
	v_pk_add_f32 v[48:49], v[164:165], v[48:49]
	v_exp_f32_e32 v71, v233
	v_pk_add_f32 v[232:233], v[42:43], v[230:231] op_sel:[0,1] op_sel_hi:[1,1] neg_lo:[0,1] neg_hi:[0,1]
	v_pk_add_f32 v[234:235], v[18:19], v[230:231] op_sel:[0,1] op_sel_hi:[1,1] neg_lo:[0,1] neg_hi:[0,1]
	v_pk_add_f32 v[236:237], v[2:3], v[230:231] op_sel:[0,1] op_sel_hi:[1,1] neg_lo:[0,1] neg_hi:[0,1]
	v_pk_add_f32 v[48:49], v[172:173], v[48:49]
	v_exp_f32_e32 v76, v232
	v_exp_f32_e32 v74, v234
	v_exp_f32_e32 v60, v236
	v_pk_add_f32 v[48:49], v[178:179], v[48:49]
	v_exp_f32_e32 v77, v233
	v_pk_add_f32 v[232:233], v[44:45], v[230:231] op_sel:[0,1] op_sel_hi:[1,1] neg_lo:[0,1] neg_hi:[0,1]
	v_exp_f32_e32 v75, v235
	v_pk_add_f32 v[234:235], v[20:21], v[230:231] op_sel:[0,1] op_sel_hi:[1,1] neg_lo:[0,1] neg_hi:[0,1]
	v_exp_f32_e32 v61, v237
	v_pk_add_f32 v[236:237], v[4:5], v[230:231] op_sel:[0,1] op_sel_hi:[1,1] neg_lo:[0,1] neg_hi:[0,1]
	v_pk_add_f32 v[32:33], v[78:79], v[48:49]
	v_exp_f32_e32 v156, v232
	v_exp_f32_e32 v98, v234
	v_exp_f32_e32 v66, v236
	v_pk_add_f32 v[32:33], v[158:159], v[32:33]
	v_exp_f32_e32 v157, v233
	v_pk_add_f32 v[232:233], v[46:47], v[230:231] op_sel:[0,1] op_sel_hi:[1,1] neg_lo:[0,1] neg_hi:[0,1]
	v_exp_f32_e32 v99, v235
	v_pk_add_f32 v[234:235], v[22:23], v[230:231] op_sel:[0,1] op_sel_hi:[1,1] neg_lo:[0,1] neg_hi:[0,1]
	v_exp_f32_e32 v67, v237
	v_pk_add_f32 v[236:237], v[6:7], v[230:231] op_sel:[0,1] op_sel_hi:[1,1] neg_lo:[0,1] neg_hi:[0,1]
	v_pk_add_f32 v[32:33], v[166:167], v[32:33]
	v_exp_f32_e32 v168, v232
	v_pk_add_f32 v[238:239], v[16:17], v[230:231] op_sel:[0,1] op_sel_hi:[1,1] neg_lo:[0,1] neg_hi:[0,1]
	v_exp_f32_e32 v160, v234
	v_exp_f32_e32 v68, v236
	v_pk_add_f32 v[32:33], v[174:175], v[32:33]
	v_exp_f32_e32 v169, v233
	v_exp_f32_e32 v64, v238
	v_exp_f32_e32 v161, v235
	v_pk_add_f32 v[232:233], v[24:25], v[230:231] op_sel:[0,1] op_sel_hi:[1,1] neg_lo:[0,1] neg_hi:[0,1]
	v_exp_f32_e32 v69, v237
	v_pk_add_f32 v[234:235], v[8:9], v[230:231] op_sel:[0,1] op_sel_hi:[1,1] neg_lo:[0,1] neg_hi:[0,1]
	v_pk_add_f32 v[32:33], v[70:71], v[32:33]
	v_exp_f32_e32 v65, v239
	v_exp_f32_e32 v58, v232
	v_exp_f32_e32 v48, v234
	v_pk_add_f32 v[32:33], v[76:77], v[32:33]
	v_exp_f32_e32 v59, v233
	v_pk_add_f32 v[232:233], v[26:27], v[230:231] op_sel:[0,1] op_sel_hi:[1,1] neg_lo:[0,1] neg_hi:[0,1]
	v_exp_f32_e32 v49, v235
	v_pk_add_f32 v[234:235], v[10:11], v[230:231] op_sel:[0,1] op_sel_hi:[1,1] neg_lo:[0,1] neg_hi:[0,1]
	v_pk_add_f32 v[32:33], v[156:157], v[32:33]
	v_exp_f32_e32 v62, v232
	v_exp_f32_e32 v50, v234
	v_pk_add_f32 v[32:33], v[168:169], v[32:33]
	v_exp_f32_e32 v63, v233
	v_pk_add_f32 v[232:233], v[28:29], v[230:231] op_sel:[0,1] op_sel_hi:[1,1] neg_lo:[0,1] neg_hi:[0,1]
	v_exp_f32_e32 v51, v235
	v_pk_add_f32 v[234:235], v[12:13], v[230:231] op_sel:[0,1] op_sel_hi:[1,1] neg_lo:[0,1] neg_hi:[0,1]
	v_pk_add_f32 v[16:17], v[64:65], v[32:33]
	v_exp_f32_e32 v72, v232
	v_exp_f32_e32 v52, v234
	v_pk_add_f32 v[16:17], v[74:75], v[16:17]
	v_exp_f32_e32 v73, v233
	v_pk_add_f32 v[232:233], v[30:31], v[230:231] op_sel:[0,1] op_sel_hi:[1,1] neg_lo:[0,1] neg_hi:[0,1]
	v_exp_f32_e32 v53, v235
	v_pk_add_f32 v[234:235], v[14:15], v[230:231] op_sel:[0,1] op_sel_hi:[1,1] neg_lo:[0,1] neg_hi:[0,1]
	v_pk_add_f32 v[16:17], v[98:99], v[16:17]
	v_exp_f32_e32 v118, v232
	v_pk_add_f32 v[236:237], v[0:1], v[230:231] op_sel:[0,1] op_sel_hi:[1,1] neg_lo:[0,1] neg_hi:[0,1]
	v_exp_f32_e32 v54, v234
	v_pk_add_f32 v[16:17], v[160:161], v[16:17]
	v_exp_f32_e32 v119, v233
	v_exp_f32_e32 v56, v236
	v_exp_f32_e32 v55, v235
	v_pk_add_f32 v[232:233], v[216:217], v[230:231] op_sel:[0,1] op_sel_hi:[1,1] neg_lo:[0,1] neg_hi:[0,1]
	v_pk_add_f32 v[16:17], v[58:59], v[16:17]
	v_exp_f32_e32 v57, v237
	v_exp_f32_e32 v40, v232
	v_sub_f32_e32 v2, v215, v231
	v_pk_add_f32 v[16:17], v[62:63], v[16:17]
	v_exp_f32_e32 v41, v2
	v_pk_add_f32 v[16:17], v[72:73], v[16:17]
	v_exp_f32_e32 v42, v233
	v_pk_add_f32 v[232:233], v[218:219], v[230:231] op_sel:[0,1] op_sel_hi:[1,1] neg_lo:[0,1] neg_hi:[0,1]
	v_pk_add_f32 v[16:17], v[118:119], v[16:17]
	v_exp_f32_e32 v43, v232
	v_pk_add_f32 v[0:1], v[56:57], v[16:17]
	v_exp_f32_e32 v44, v233
	v_pk_add_f32 v[232:233], v[220:221], v[230:231] op_sel:[0,1] op_sel_hi:[1,1] neg_lo:[0,1] neg_hi:[0,1]
	v_pk_add_f32 v[0:1], v[60:61], v[0:1]
	v_exp_f32_e32 v45, v232
	v_pk_add_f32 v[0:1], v[66:67], v[0:1]
	v_exp_f32_e32 v46, v233
	v_pk_add_f32 v[232:233], v[222:223], v[230:231] op_sel:[0,1] op_sel_hi:[1,1] neg_lo:[0,1] neg_hi:[0,1]
	v_pk_add_f32 v[0:1], v[68:69], v[0:1]
	v_exp_f32_e32 v47, v232
	v_pk_add_f32 v[0:1], v[48:49], v[0:1]
	v_exp_f32_e32 v32, v233
	v_pk_add_f32 v[232:233], v[224:225], v[230:231] op_sel:[0,1] op_sel_hi:[1,1] neg_lo:[0,1] neg_hi:[0,1]
	v_pk_add_f32 v[0:1], v[50:51], v[0:1]
	v_exp_f32_e32 v33, v232
	v_pk_add_f32 v[0:1], v[52:53], v[0:1]
	v_exp_f32_e32 v34, v233
	v_pk_add_f32 v[232:233], v[226:227], v[230:231] op_sel:[0,1] op_sel_hi:[1,1] neg_lo:[0,1] neg_hi:[0,1]
	v_pk_add_f32 v[0:1], v[54:55], v[0:1]
	v_exp_f32_e32 v35, v232
	v_pk_add_f32 v[0:1], v[40:41], v[0:1]
	v_exp_f32_e32 v36, v233
	v_pk_add_f32 v[232:233], v[228:229], v[230:231] op_sel:[0,1] op_sel_hi:[1,1] neg_lo:[0,1] neg_hi:[0,1]
	v_pk_add_f32 v[0:1], v[42:43], v[0:1]
	v_exp_f32_e32 v37, v232
	v_pk_add_f32 v[0:1], v[44:45], v[0:1]
	v_exp_f32_e32 v38, v233
	v_sub_f32_e32 v2, v230, v231
	v_pk_add_f32 v[0:1], v[46:47], v[0:1]
	v_exp_f32_e32 v39, v2
	v_pk_add_f32 v[0:1], v[32:33], v[0:1]
	v_cvt_pk_bf16_f32 v16, v162, v163
	v_cvt_pk_bf16_f32 v17, v170, v171
	v_add_u32_e32 v170, 0x9000, v197
	v_pk_add_f32 v[0:1], v[34:35], v[0:1]
	v_cvt_pk_bf16_f32 v18, v176, v177
	v_cvt_pk_bf16_f32 v19, v180, v181
	v_add_u32_e32 v176, 0xd000, v197
	v_pk_add_f32 v[0:1], v[36:37], v[0:1]
	ds_read2_b64 v[20:23], v176 offset0:32 offset1:34
	v_pk_add_f32 v[0:1], v[38:39], v[0:1]
	v_lshl_add_u64 v[116:117], v[146:147], 0, s[94:95]
	v_add_f32_e32 v0, v0, v1
	v_mov_b32_e32 v142, v0
	v_mov_b32_e32 v143, v0
	s_nop 1
	v_permlane32_swap_b32_e32 v142, v143
	s_mov_b32 s97, s0
	v_readlane_b32 s0, v255, 15
	s_waitcnt lgkmcnt(0)
	v_add_f32_e32 v0, v142, v143
	v_fma_f32 v1, v214, s55, -v231
	v_exp_f32_e32 v1, v1
	s_nop 0
	v_add_f32_e32 v214, v1, v0
	ds_read2_b64 v[0:3], v170 offset1:2
	v_cvt_pk_bf16_f32 v162, v154, v155
	v_cvt_pk_bf16_f32 v163, v164, v165
	v_cvt_pk_bf16_f32 v164, v172, v173
	v_cvt_pk_bf16_f32 v165, v178, v179
	ds_read2_b64 v[170:173], v170 offset0:4 offset1:6
	s_waitcnt lgkmcnt(1)
	v_mfma_f32_32x32x16_bf16 v[0:15], v[0:3], v[16:19], 0
	s_waitcnt lgkmcnt(0)
	v_mfma_f32_32x32x16_bf16 v[0:15], v[170:173], v[162:165], v[0:15]
	ds_read2_b64 v[170:173], v176 offset0:36 offset1:38
	v_mfma_f32_32x32x16_bf16 v[16:31], v[20:23], v[16:19], 0
	s_waitcnt lgkmcnt(0)
	v_mfma_f32_32x32x16_bf16 v[16:31], v[170:173], v[162:165], v[16:31]
	v_cvt_pk_bf16_f32 v162, v78, v79
	v_add_u32_e32 v78, 0x9000, v198
	v_cvt_pk_bf16_f32 v163, v158, v159
	v_cvt_pk_bf16_f32 v164, v166, v167
	v_cvt_pk_bf16_f32 v165, v174, v175
	ds_read2_b64 v[170:173], v78 offset1:2
	v_add_u32_e32 v158, 0xd000, v198
	s_waitcnt lgkmcnt(0)
	v_mfma_f32_32x32x16_bf16 v[0:15], v[170:173], v[162:165], v[0:15]
	ds_read2_b64 v[170:173], v158 offset0:32 offset1:34
	v_cvt_pk_bf16_f32 v154, v70, v71
	v_cvt_pk_bf16_f32 v155, v76, v77
	v_cvt_pk_bf16_f32 v156, v156, v157
	v_cvt_pk_bf16_f32 v157, v168, v169
	ds_read2_b64 v[76:79], v78 offset0:4 offset1:6
	s_waitcnt lgkmcnt(0)
	v_mfma_f32_32x32x16_bf16 v[0:15], v[76:79], v[154:157], v[0:15]
	ds_read2_b64 v[76:79], v158 offset0:36 offset1:38
	v_mfma_f32_32x32x16_bf16 v[16:31], v[170:173], v[162:165], v[16:31]
	s_waitcnt lgkmcnt(0)
	v_mfma_f32_32x32x16_bf16 v[16:31], v[76:79], v[154:157], v[16:31]
	v_cvt_pk_bf16_f32 v76, v64, v65
	v_add_u32_e32 v64, 0x9000, v199
	v_cvt_pk_bf16_f32 v77, v74, v75
	v_cvt_pk_bf16_f32 v78, v98, v99
	v_cvt_pk_bf16_f32 v79, v160, v161
	ds_read2_b64 v[154:157], v64 offset1:2
	v_add_u32_e32 v74, 0xd000, v199
	s_waitcnt lgkmcnt(0)
	v_mfma_f32_32x32x16_bf16 v[0:15], v[154:157], v[76:79], v[0:15]
	ds_read2_b64 v[154:157], v74 offset0:32 offset1:34
	v_cvt_pk_bf16_f32 v70, v58, v59
	v_cvt_pk_bf16_f32 v71, v62, v63
	v_cvt_pk_bf16_f32 v72, v72, v73
	v_cvt_pk_bf16_f32 v73, v118, v119
	ds_read2_b64 v[62:65], v64 offset0:4 offset1:6
	v_or_b32_e32 v118, s0, v153
	s_waitcnt lgkmcnt(0)
	v_mfma_f32_32x32x16_bf16 v[0:15], v[62:65], v[70:73], v[0:15]
	ds_read2_b64 v[62:65], v74 offset0:36 offset1:38
	v_cvt_pk_bf16_f32 v56, v56, v57
	v_cvt_pk_bf16_f32 v57, v60, v61
	v_cvt_pk_bf16_f32 v58, v66, v67
	v_cvt_pk_bf16_f32 v59, v68, v69
	v_and_b32_e32 v67, 0xffff0000, v103
	v_and_b32_e32 v66, 0xffff0000, v107
	v_mfma_f32_32x32x16_bf16 v[16:31], v[154:157], v[76:79], v[16:31]
	v_lshlrev_b32_e32 v155, 16, v100
	v_lshlrev_b32_e32 v154, 16, v104
	v_and_b32_e32 v79, 0xffff0000, v102
	v_mul_f32_e64 v156, v154, v154
	v_mul_f32_e64 v157, v155, v155
	v_and_b32_e32 v78, 0xffff0000, v106
	v_pk_mul_f32 v[98:99], v[78:79], v[78:79]
	v_pk_mul_f32 v[68:69], v[66:67], v[66:67]
	s_waitcnt lgkmcnt(0)
	v_mfma_f32_32x32x16_bf16 v[16:31], v[62:65], v[70:73], v[16:31]
	v_add_u32_e32 v64, 0x9000, v200
	ds_read2_b64 v[60:63], v64 offset1:2
	v_add_u32_e32 v65, 0xd000, v200
	v_lshlrev_b32_e32 v71, 16, v102
	v_lshlrev_b32_e32 v102, 16, v105
	v_lshlrev_b32_e32 v70, 16, v106
	v_pk_mul_f32 v[72:73], v[70:71], v[70:71]
	s_waitcnt lgkmcnt(0)
	v_mfma_f32_32x32x16_bf16 v[0:15], v[60:63], v[56:59], v[0:15]
	ds_read2_b64 v[60:63], v65 offset0:32 offset1:34
	v_cvt_pk_bf16_f32 v48, v48, v49
	v_cvt_pk_bf16_f32 v49, v50, v51
	v_cvt_pk_bf16_f32 v50, v52, v53
	v_cvt_pk_bf16_f32 v51, v54, v55
	ds_read2_b64 v[52:55], v64 offset0:4 offset1:6
	s_waitcnt lgkmcnt(0)
	v_mfma_f32_32x32x16_bf16 v[0:15], v[52:55], v[48:51], v[0:15]
	ds_read2_b64 v[52:55], v65 offset0:36 offset1:38
	v_cvt_pk_bf16_f32 v40, v40, v41
	v_cvt_pk_bf16_f32 v41, v42, v43
	v_cvt_pk_bf16_f32 v42, v44, v45
	v_cvt_pk_bf16_f32 v43, v46, v47
	v_mfma_f32_32x32x16_bf16 v[16:31], v[60:63], v[56:59], v[16:31]
	v_lshlrev_b32_e32 v59, 16, v103
	v_lshlrev_b32_e32 v103, 16, v101
	v_lshlrev_b32_e32 v58, 16, v107
	v_mul_f32_e64 v106, v102, v102
	v_mul_f32_e64 v107, v103, v103
	v_pk_mul_f32 v[60:61], v[58:59], v[58:59]
	s_waitcnt lgkmcnt(0)
	v_mfma_f32_32x32x16_bf16 v[16:31], v[52:55], v[48:51], v[16:31]
	v_add_u32_e32 v48, 0x9000, v201
	ds_read2_b64 v[44:47], v48 offset1:2
	v_add_u32_e32 v49, 0xd000, v201
	s_waitcnt lgkmcnt(0)
	v_mfma_f32_32x32x16_bf16 v[0:15], v[44:47], v[40:43], v[0:15]
	ds_read2_b64 v[44:47], v49 offset0:32 offset1:34
	v_cvt_pk_bf16_f32 v32, v32, v33
	v_cvt_pk_bf16_f32 v33, v34, v35
	v_cvt_pk_bf16_f32 v34, v36, v37
	v_cvt_pk_bf16_f32 v35, v38, v39
	ds_read2_b64 v[36:39], v48 offset0:4 offset1:6
	s_waitcnt lgkmcnt(0)
	v_mfma_f32_32x32x16_bf16 v[0:15], v[36:39], v[32:35], v[0:15]
	ds_read2_b64 v[36:39], v49 offset0:36 offset1:38
	v_mfma_f32_32x32x16_bf16 v[16:31], v[44:47], v[40:43], v[16:31]
	v_lshlrev_b32_e32 v42, 16, v112
	v_lshlrev_b32_e32 v43, 16, v108
	v_mul_f32_e64 v54, v42, v42
	v_mul_f32_e64 v55, v43, v43
	s_waitcnt lgkmcnt(0)
	v_mfma_f32_32x32x16_bf16 v[16:31], v[36:39], v[32:35], v[16:31]
	v_div_scale_f32 v32, s[68:69], v214, v214, 1.0
	v_rcp_f32_e32 v33, v32
	v_lshlrev_b32_e32 v38, 16, v113
	v_mov_b32_e32 v41, v38
	v_lshlrev_b32_e32 v39, 16, v109
	v_fma_f32 v34, -v32, v33, 1.0
	v_fmac_f32_e32 v33, v34, v33
	v_div_scale_f32 v34, vcc, 1.0, v214, 1.0
	v_mul_f32_e32 v35, v34, v33
	v_fma_f32 v36, -v32, v35, v34
	v_fmac_f32_e32 v35, v36, v33
	v_fma_f32 v32, -v32, v35, v34
	v_div_fmas_f32 v32, v32, v33, v35
	v_div_fixup_f32 v34, v32, v214, 1.0
	v_mul_f32_e32 v0, v0, v34
	v_mul_f32_e32 v1, v1, v34
	v_cvt_pk_bf16_f32 v0, v0, v1
	v_mul_f32_e32 v1, v2, v34
	v_mad_i64_i32 v[32:33], s[68:69], v213, s65, v[116:117]
	v_and_b32_e32 v36, 63, v251
	v_and_b32_e32 v35, 31, v251
	v_lshrrev_b32_e32 v37, 5, v36
	v_lshlrev_b32_e32 v37, 3, v37
	s_movk_i32 s58, 0x90
	v_mad_u32_u24 v35, v35, s58, v37
	s_movk_i32 s59, 0x1200
	v_mad_u32_u24 v35, v254, s59, v35
	v_add_u32_e32 v35, 0x12000, v35
	v_lshrrev_b32_e32 v37, 3, v36
	v_and_b32_e32 v40, 7, v36
	v_lshlrev_b32_e32 v40, 4, v40
	v_mad_u32_u24 v36, v37, s58, v40
	v_mad_u32_u24 v36, v254, s59, v36
	v_add_u32_e32 v36, 0x12000, v36
	s_movk_i32 s58, 0xc00
	v_mad_u32_u24 v37, v37, s58, v40
	v_readfirstlane_b32 s56, v32
	v_readfirstlane_b32 s57, v33
	v_mul_f32_e32 v2, v3, v34
	v_cvt_pk_bf16_f32 v1, v1, v2
	ds_write_b64 v35, v[0:1]
	v_mul_f32_e32 v0, v4, v34
	v_mul_f32_e32 v1, v5, v34
	v_cvt_pk_bf16_f32 v0, v0, v1
	v_mul_f32_e32 v1, v6, v34
	v_mul_f32_e32 v2, v7, v34
	v_cvt_pk_bf16_f32 v1, v1, v2
	ds_write_b64 v35, v[0:1] offset:16
	v_mul_f32_e32 v0, v8, v34
	v_mul_f32_e32 v1, v9, v34
	v_cvt_pk_bf16_f32 v0, v0, v1
	v_mul_f32_e32 v1, v10, v34
	v_mul_f32_e32 v2, v11, v34
	v_cvt_pk_bf16_f32 v1, v1, v2
	ds_write_b64 v35, v[0:1] offset:32
	v_mul_f32_e32 v0, v12, v34
	v_mul_f32_e32 v1, v13, v34
	v_cvt_pk_bf16_f32 v0, v0, v1
	v_mul_f32_e32 v1, v14, v34
	v_mul_f32_e32 v2, v15, v34
	v_cvt_pk_bf16_f32 v1, v1, v2
	ds_write_b64 v35, v[0:1] offset:48
	v_mul_f32_e32 v0, v16, v34
	v_mul_f32_e32 v1, v17, v34
	v_cvt_pk_bf16_f32 v0, v0, v1
	v_mul_f32_e32 v1, v18, v34
	v_mul_f32_e32 v2, v19, v34
	v_cvt_pk_bf16_f32 v1, v1, v2
	ds_write_b64 v35, v[0:1] offset:64
	v_mul_f32_e32 v0, v20, v34
	v_mul_f32_e32 v1, v21, v34
	v_cvt_pk_bf16_f32 v0, v0, v1
	v_mul_f32_e32 v1, v22, v34
	v_mul_f32_e32 v2, v23, v34
	v_cvt_pk_bf16_f32 v1, v1, v2
	ds_write_b64 v35, v[0:1] offset:80
	v_mul_f32_e32 v0, v24, v34
	v_mul_f32_e32 v1, v25, v34
	v_cvt_pk_bf16_f32 v0, v0, v1
	v_mul_f32_e32 v1, v26, v34
	v_mul_f32_e32 v2, v27, v34
	v_cvt_pk_bf16_f32 v1, v1, v2
	ds_write_b64 v35, v[0:1] offset:96
	v_mul_f32_e32 v0, v28, v34
	v_mul_f32_e32 v1, v29, v34
	v_cvt_pk_bf16_f32 v0, v0, v1
	v_mul_f32_e32 v1, v30, v34
	v_mul_f32_e32 v2, v31, v34
	v_cvt_pk_bf16_f32 v1, v1, v2
	ds_write_b64 v35, v[0:1] offset:112
	s_waitcnt lgkmcnt(0)
	ds_read_b128 v[0:3], v36
	ds_read_b128 v[4:7], v36 offset:1152
	ds_read_b128 v[8:11], v36 offset:2304
	ds_read_b128 v[12:15], v36 offset:3456
	s_waitcnt lgkmcnt(3)
	global_store_dwordx4 v37, v[0:3], s[56:57]
	s_add_u32 s56, s56, 0x6000
	s_addc_u32 s57, s57, 0
	s_waitcnt lgkmcnt(2)
	global_store_dwordx4 v37, v[4:7], s[56:57]
	s_add_u32 s56, s56, 0x6000
	s_addc_u32 s57, s57, 0
	s_waitcnt lgkmcnt(1)
	global_store_dwordx4 v37, v[8:11], s[56:57]
	s_add_u32 s56, s56, 0x6000
	s_addc_u32 s57, s57, 0
	s_waitcnt lgkmcnt(0)
	global_store_dwordx4 v37, v[12:15], s[56:57]
	s_nop 1
	s_and_b64 vcc, exec, s[76:77]
	s_cbranch_vccnz .Lvpf_skip
	s_lshl_b32 s58, s33, 5
	s_and_b32 s58, s58, 0x780
	s_addk_i32 s58, 0xff80
	v_add_u32_e32 v16, s58, v183
	v_cmp_lt_i32_e32 vcc, -1, v16
	v_mov_b32_e32 v122, 0
	v_mov_b32_e32 v123, 0
	v_mov_b32_e32 v124, 0
	v_mov_b32_e32 v125, 0
	v_mov_b32_e32 v128, 0
	v_mov_b32_e32 v129, 0
	v_mov_b32_e32 v130, 0
	v_mov_b32_e32 v131, 0
	v_mov_b32_e32 v132, 0
	v_mov_b32_e32 v133, 0
	v_mov_b32_e32 v134, 0
	v_mov_b32_e32 v135, 0
	v_mov_b32_e32 v136, 0
	v_mov_b32_e32 v137, 0
	v_mov_b32_e32 v138, 0
	v_mov_b32_e32 v139, 0
	s_and_saveexec_b64 s[80:81], vcc
	s_cbranch_execz .Lvpf_join
	v_readlane_b32 vcc_lo, v255, 6
	v_readlane_b32 vcc_hi, v255, 7
	s_ashr_i32 s59, s33, 6
	v_add_u32_e32 v18, s58, v250
	v_lshl_add_u32 v18, s59, 11, v18
	s_and_b32 s58, s33, 3
	s_lshl_b32 s58, s58, 7
	s_mov_b32 s59, 0
	v_mov_b64_e32 v[16:17], vcc
	v_mad_i64_i32 v[16:17], vcc, v18, s65, v[16:17]
	v_lshl_add_u64 v[16:17], v[16:17], 0, s[58:59]
	v_lshl_add_u64 v[16:17], v[16:17], 0, v[248:249]
	s_movk_i32 s58, 0x6000
	global_load_dwordx4 v[122:125], v[16:17], off offset:2560
	v_lshl_add_u64 v[16:17], v[16:17], 0, s[58:59]
	global_load_dwordx4 v[128:131], v[16:17], off offset:2560
	v_lshl_add_u64 v[16:17], v[16:17], 0, s[58:59]
	global_load_dwordx4 v[132:135], v[16:17], off offset:2560
	v_lshl_add_u64 v[16:17], v[16:17], 0, s[58:59]
	global_load_dwordx4 v[136:139], v[16:17], off offset:2560

.Lvpf_skip:
	ds_read_b128 v[0:3], v243 offset:16
	s_nop 0
	ds_read_b128 v[16:19], v243
	ds_read_b128 v[4:7], v243 offset:144
	ds_read_b128 v[20:23], v243 offset:128
	v_lshlrev_b32_e32 v28, 5, v118
	v_or_b32_e32 v8, v28, v126
	v_lshlrev_b32_e32 v29, 2, v8
	ds_read_b128 v[8:11], v252 offset:6144
	ds_read_b128 v[24:27], v252 offset:2048
	ds_read_b128 v[12:15], v252 offset:24192
	ds_read_b128 v[44:47], v252 offset:20096
	v_or_b32_e32 v28, v28, v127
	v_lshlrev_b32_e32 v119, 2, v28
	v_lshlrev_b32_e32 v30, 16, v115
	v_and_b32_e32 v28, 0xffff0000, v115
	v_mov_b32_e32 v32, v28
	v_mov_b32_e32 v33, v30
	v_pk_mul_f32 v[48:49], v[32:33], v[32:33]
	v_lshlrev_b32_e32 v34, 16, v114
	v_and_b32_e32 v32, 0xffff0000, v114
	v_mov_b32_e32 v36, v32
	v_mov_b32_e32 v37, v34
	v_pk_mul_f32 v[50:51], v[36:37], v[36:37]
	v_and_b32_e32 v36, 0xffff0000, v113
	v_mov_b32_e32 v40, v36
	v_and_b32_e32 v113, 0xffff0000, v101
	v_and_b32_e32 v101, 0xffff0000, v100
	v_and_b32_e32 v100, 0xffff0000, v104
	v_pk_mul_f32 v[52:53], v[40:41], v[40:41]
	v_and_b32_e32 v40, 0xffff0000, v112
	v_and_b32_e32 v112, 0xffff0000, v105
	v_pk_mul_f32 v[104:105], v[100:101], v[100:101]
	v_pk_mul_f32 v[114:115], v[112:113], v[112:113]
	v_and_b32_e32 v41, 0xffff0000, v108
	v_pk_mul_f32 v[56:57], v[40:41], v[40:41]
	v_and_b32_e32 v37, 0xffff0000, v109
	v_lshlrev_b32_e32 v35, 16, v110
	v_and_b32_e32 v33, 0xffff0000, v110
	v_lshlrev_b32_e32 v31, 16, v111
	v_and_b32_e32 v29, 0xffff0000, v111
	s_andn2_b64 vcc, exec, s[78:79]
	s_waitcnt lgkmcnt(0)
	v_mov_b32_e32 v75, v0
	v_add_f32_e32 v0, v157, v105
	v_add_f32_e32 v0, v107, v0
	v_add_f32_e32 v0, v115, v0
	v_add_f32_e32 v0, v73, v0
	v_add_f32_e32 v0, v99, v0
	v_add_f32_e32 v0, v61, v0
	v_add_f32_e32 v0, v69, v0
	v_add_f32_e32 v0, v55, v0
	v_add_f32_e32 v0, v57, v0
	v_fmac_f32_e32 v0, v39, v39
	v_fmac_f32_e32 v0, v37, v37
	v_fmac_f32_e32 v0, v35, v35
	v_fmac_f32_e32 v0, v33, v33
	v_fmac_f32_e32 v0, v31, v31
	v_fmac_f32_e32 v0, v29, v29
	v_add_f32_e32 v0, v156, v0
	v_add_f32_e32 v0, v104, v0
	v_add_f32_e32 v0, v106, v0
	v_add_f32_e32 v0, v114, v0
	v_add_f32_e32 v0, v72, v0
	v_add_f32_e32 v0, v98, v0
	v_add_f32_e32 v0, v60, v0
	v_add_f32_e32 v0, v68, v0
	v_add_f32_e32 v0, v54, v0
	v_add_f32_e32 v0, v56, v0
	v_add_f32_e32 v0, v53, v0
	v_add_f32_e32 v0, v52, v0
	v_add_f32_e32 v0, v51, v0
	v_add_f32_e32 v0, v50, v0
	v_add_f32_e32 v0, v49, v0
	v_add_f32_e32 v0, v48, v0
	v_mov_b32_e32 v63, v2
	v_mov_b32_e32 v142, v0
	v_mov_b32_e32 v143, v0
	s_nop 1
	v_permlane32_swap_b32_e32 v142, v143
	s_waitcnt lgkmcnt(0)
	v_mov_b32_e32 v74, v4
	s_waitcnt lgkmcnt(0)
	v_mov_b32_e32 v158, v20
	s_waitcnt lgkmcnt(0)
	v_mov_b32_e32 v159, v16
	v_mov_b32_e32 v160, v24
	s_waitcnt lgkmcnt(0)
	v_add_f32_e32 v0, v142, v143
	v_fmamk_f32 v0, v0, 0x3c800000, v189
	v_rsq_f32_e32 v0, v0
	v_mov_b32_e32 v161, v44
	v_mov_b32_e32 v50, v44
	v_mov_b32_e32 v51, v24
	v_mul_f32_e32 v4, 0x3e38aa3b, v0
	v_pk_mul_f32 v[48:49], v[4:5], v[154:155] op_sel_hi:[0,1]
	v_pk_mul_f32 v[48:49], v[158:159], v[48:49]
	v_mov_b32_e32 v108, v22
	v_pk_mul_f32 v[50:51], v[50:51], v[48:49]
	v_pk_mul_f32 v[48:49], v[160:161], v[48:49]
	v_mov_b32_e32 v16, v21
	v_add_f32_e32 v22, v48, v49
	v_pk_mul_f32 v[48:49], v[4:5], v[100:101] op_sel_hi:[0,1]
	v_pk_mul_f32 v[16:17], v[16:17], v[48:49]
	v_mov_b32_e32 v24, v45
	v_mov_b32_e32 v44, v25
	v_pk_mul_f32 v[20:21], v[24:25], v[16:17]
	v_pk_mul_f32 v[16:17], v[44:45], v[16:17]
	v_mov_b32_e32 v109, v18
	v_add_f32_e32 v25, v16, v17
	v_pk_mul_f32 v[16:17], v[4:5], v[102:103] op_sel_hi:[0,1]
	v_mov_b32_e32 v110, v26
	v_mov_b32_e32 v111, v46
	v_sub_f32_e32 v24, v21, v20
	v_pk_mul_f32 v[16:17], v[16:17], v[108:109]
	v_mov_b32_e32 v20, v46
	v_mov_b32_e32 v21, v26
	v_pk_mul_f32 v[20:21], v[16:17], v[20:21]
	v_pk_mul_f32 v[16:17], v[16:17], v[110:111]
	v_sub_f32_e32 v20, v21, v20
	v_add_f32_e32 v21, v16, v17
	v_pk_mul_f32 v[16:17], v[4:5], v[112:113] op_sel_hi:[0,1]
	v_mov_b32_e32 v18, v23
	v_pk_mul_f32 v[16:17], v[16:17], v[18:19]
	v_mov_b32_e32 v26, v47
	v_mov_b32_e32 v46, v27
	v_pk_mul_f32 v[18:19], v[16:17], v[26:27]
	v_pk_mul_f32 v[16:17], v[16:17], v[46:47]
	v_mov_b32_e32 v76, v8
	v_add_f32_e32 v26, v16, v17
	v_pk_mul_f32 v[16:17], v[4:5], v[70:71] op_sel_hi:[0,1]
	v_mov_b32_e32 v77, v12
	v_sub_f32_e32 v23, v19, v18
	v_pk_mul_f32 v[16:17], v[16:17], v[74:75]
	v_mov_b32_e32 v18, v12
	v_mov_b32_e32 v19, v8
	v_pk_mul_f32 v[18:19], v[16:17], v[18:19]
	v_pk_mul_f32 v[16:17], v[16:17], v[76:77]
	v_sub_f32_e32 v18, v19, v18
	v_add_f32_e32 v19, v16, v17
	v_pk_mul_f32 v[16:17], v[4:5], v[78:79] op_sel_hi:[0,1]
	v_mov_b32_e32 v0, v5
	v_pk_mul_f32 v[0:1], v[16:17], v[0:1]
	v_mov_b32_e32 v8, v13
	v_pk_mul_f32 v[16:17], v[0:1], v[8:9]
	v_mov_b32_e32 v12, v9
	v_sub_f32_e32 v5, v17, v16
	v_pk_mul_f32 v[0:1], v[0:1], v[12:13]
	v_mov_b32_e32 v62, v6
	v_add_f32_e32 v12, v0, v1
	v_pk_mul_f32 v[0:1], v[4:5], v[58:59] op_sel_hi:[0,1]
	v_mov_b32_e32 v64, v10
	v_mov_b32_e32 v65, v14
	v_pk_mul_f32 v[0:1], v[0:1], v[62:63]
	v_mov_b32_e32 v8, v14
	v_mov_b32_e32 v9, v10
	v_pk_mul_f32 v[8:9], v[0:1], v[8:9]
	v_pk_mul_f32 v[0:1], v[0:1], v[64:65]
	v_sub_f32_e32 v8, v9, v8
	v_add_f32_e32 v9, v0, v1
	v_pk_mul_f32 v[0:1], v[4:5], v[66:67] op_sel_hi:[0,1]
	v_mov_b32_e32 v2, v7
	v_pk_mul_f32 v[0:1], v[0:1], v[2:3]
	v_mov_b32_e32 v10, v15
	v_mov_b32_e32 v14, v11
	v_pk_mul_f32 v[2:3], v[0:1], v[10:11]
	v_pk_mul_f32 v[0:1], v[0:1], v[14:15]
	v_sub_f32_e32 v6, v51, v50
	v_sub_f32_e32 v2, v3, v2
	v_add_f32_e32 v0, v0, v1
	v_cvt_pk_bf16_f32 v48, v6, v24
	v_cvt_pk_bf16_f32 v49, v20, v23
	v_cvt_pk_bf16_f32 v50, v18, v5
	v_cvt_pk_bf16_f32 v51, v8, v2
	v_cvt_pk_bf16_f32 v98, v22, v25
	v_cvt_pk_bf16_f32 v99, v21, v26
	v_cvt_pk_bf16_f32 v100, v19, v12
	v_cvt_pk_bf16_f32 v101, v9, v0
	ds_read_b128 v[0:3], v243 offset:80
	ds_read_b128 v[6:9], v243 offset:64
	ds_read_b128 v[10:13], v243 offset:208
	ds_read_b128 v[14:17], v243 offset:192
	v_pk_mul_f32 v[18:19], v[4:5], v[42:43] op_sel_hi:[0,1]
	s_waitcnt lgkmcnt(0)
	v_mov_b32_e32 v21, v6
	s_waitcnt lgkmcnt(0)
	v_mov_b32_e32 v20, v14
	v_pk_mul_f32 v[26:27], v[18:19], v[20:21]
	ds_read_b128 v[18:21], v252 offset:14336
	ds_read_b128 v[22:25], v252 offset:10240
	ds_read_b128 v[42:45], v252 offset:32384
	ds_read_b128 v[52:55], v252 offset:28288
	v_mov_b32_e32 v6, v15
	s_waitcnt lgkmcnt(0)
	v_mov_b32_e32 v47, v22
	s_waitcnt lgkmcnt(0)
	v_mov_b32_e32 v46, v52
	v_pk_mul_f32 v[46:47], v[26:27], v[46:47]
	s_nop 0
	v_sub_f32_e32 v5, v47, v46
	v_mov_b32_e32 v46, v22
	v_mov_b32_e32 v47, v52
	v_pk_mul_f32 v[26:27], v[26:27], v[46:47]
	v_mov_b32_e32 v22, v53
	v_add_f32_e32 v46, v26, v27
	v_pk_mul_f32 v[26:27], v[4:5], v[40:41] op_sel_hi:[0,1]
	v_pk_mul_f32 v[6:7], v[26:27], v[6:7]
	v_mov_b32_e32 v52, v23
	v_pk_mul_f32 v[14:15], v[6:7], v[22:23]
	v_pk_mul_f32 v[6:7], v[6:7], v[52:53]
	v_sub_f32_e32 v22, v15, v14
	v_add_f32_e32 v23, v6, v7
	v_pk_mul_f32 v[6:7], v[4:5], v[38:39] op_sel_hi:[0,1]
	v_mov_b32_e32 v14, v16
	v_mov_b32_e32 v15, v8
	v_pk_mul_f32 v[6:7], v[6:7], v[14:15]
	v_mov_b32_e32 v14, v54
	v_mov_b32_e32 v15, v24
	v_pk_mul_f32 v[14:15], v[6:7], v[14:15]
	v_mov_b32_e32 v8, v17
	v_sub_f32_e32 v16, v15, v14
	v_mov_b32_e32 v14, v24
	v_mov_b32_e32 v15, v54
	v_pk_mul_f32 v[6:7], v[6:7], v[14:15]
	v_mov_b32_e32 v24, v55
	v_add_f32_e32 v14, v6, v7
	v_pk_mul_f32 v[6:7], v[4:5], v[36:37] op_sel_hi:[0,1]
	v_pk_mul_f32 v[6:7], v[6:7], v[8:9]
	v_mov_b32_e32 v54, v25
	v_pk_mul_f32 v[8:9], v[6:7], v[24:25]
	v_pk_mul_f32 v[6:7], v[6:7], v[54:55]
	v_sub_f32_e32 v15, v9, v8
	v_add_f32_e32 v17, v6, v7
	v_pk_mul_f32 v[6:7], v[4:5], v[34:35] op_sel_hi:[0,1]
	s_waitcnt lgkmcnt(0)
	v_mov_b32_e32 v8, v10
	s_waitcnt lgkmcnt(0)
	v_mov_b32_e32 v9, v0
	v_pk_mul_f32 v[6:7], v[6:7], v[8:9]
	v_mov_b32_e32 v8, v42
	v_mov_b32_e32 v9, v18
	v_pk_mul_f32 v[8:9], v[6:7], v[8:9]
	v_mov_b32_e32 v0, v11
	v_sub_f32_e32 v10, v9, v8
	v_mov_b32_e32 v8, v18
	v_mov_b32_e32 v9, v42
	v_pk_mul_f32 v[6:7], v[6:7], v[8:9]
	v_mov_b32_e32 v18, v43
	v_add_f32_e32 v8, v6, v7
	v_pk_mul_f32 v[6:7], v[4:5], v[32:33] op_sel_hi:[0,1]
	v_pk_mul_f32 v[0:1], v[6:7], v[0:1]
	v_mov_b32_e32 v42, v19
	v_pk_mul_f32 v[6:7], v[0:1], v[18:19]
	v_pk_mul_f32 v[0:1], v[0:1], v[42:43]
	v_sub_f32_e32 v9, v7, v6
	v_add_f32_e32 v11, v0, v1
	v_pk_mul_f32 v[0:1], v[4:5], v[30:31] op_sel_hi:[0,1]
	v_mov_b32_e32 v6, v12
	v_mov_b32_e32 v7, v2
	v_pk_mul_f32 v[0:1], v[0:1], v[6:7]
	v_mov_b32_e32 v6, v44
	v_mov_b32_e32 v7, v20
	v_pk_mul_f32 v[6:7], v[0:1], v[6:7]
	v_mov_b32_e32 v2, v13
	v_sub_f32_e32 v12, v7, v6
	v_mov_b32_e32 v6, v20
	v_mov_b32_e32 v7, v44
	v_pk_mul_f32 v[0:1], v[0:1], v[6:7]
	v_mov_b32_e32 v20, v45
	v_add_f32_e32 v6, v0, v1
	v_pk_mul_f32 v[0:1], v[4:5], v[28:29] op_sel_hi:[0,1]
	v_pk_mul_f32 v[0:1], v[0:1], v[2:3]
	v_mov_b32_e32 v44, v21
	v_pk_mul_f32 v[2:3], v[0:1], v[20:21]
	v_pk_mul_f32 v[0:1], v[0:1], v[44:45]
	v_sub_f32_e32 v2, v3, v2
	v_add_f32_e32 v0, v0, v1
	v_cvt_pk_bf16_f32 v102, v5, v22
	v_cvt_pk_bf16_f32 v103, v16, v15
	v_cvt_pk_bf16_f32 v104, v10, v9
	v_cvt_pk_bf16_f32 v105, v12, v2
	v_cvt_pk_bf16_f32 v106, v46, v23
	v_cvt_pk_bf16_f32 v107, v14, v17
	v_cvt_pk_bf16_f32 v108, v8, v11
	v_cvt_pk_bf16_f32 v109, v6, v0
	ds_read_b128 v[0:3], v202
	ds_read_b128 v[4:7], v202 offset:32
	s_waitcnt lgkmcnt(1)
	v_mfma_f32_32x32x16_bf16 v[64:79], v[0:3], v[48:51], 0
	ds_read_b128 v[0:3], v202 offset:64
	s_waitcnt lgkmcnt(1)
	v_mfma_f32_32x32x16_bf16 v[64:79], v[4:7], v[102:105], v[64:79]
	s_waitcnt lgkmcnt(0)
	v_mfma_f32_32x32x16_bf16 v[64:79], v[0:3], v[98:101], v[64:79]
	ds_read_b128 v[0:3], v202 offset:96
	s_waitcnt lgkmcnt(0)
	v_mfma_f32_32x32x16_bf16 v[64:79], v[0:3], v[106:109], v[64:79]
	ds_read_b128 v[0:3], v203
	ds_read_b128 v[4:7], v203 offset:32
	s_waitcnt lgkmcnt(1)
	v_mfma_f32_32x32x16_bf16 v[32:47], v[0:3], v[48:51], 0
	ds_read_b128 v[0:3], v203 offset:64
	s_waitcnt lgkmcnt(1)
	v_mfma_f32_32x32x16_bf16 v[32:47], v[4:7], v[102:105], v[32:47]
	s_waitcnt lgkmcnt(0)
	v_mfma_f32_32x32x16_bf16 v[32:47], v[0:3], v[98:101], v[32:47]
	ds_read_b128 v[0:3], v203 offset:96
	s_waitcnt lgkmcnt(0)
	v_mfma_f32_32x32x16_bf16 v[32:47], v[0:3], v[106:109], v[32:47]
	ds_read_b128 v[0:3], v204
	ds_read_b128 v[4:7], v204 offset:32
	s_waitcnt lgkmcnt(1)
	v_mfma_f32_32x32x16_bf16 v[16:31], v[0:3], v[48:51], 0
	ds_read_b128 v[0:3], v204 offset:64
	s_waitcnt lgkmcnt(1)
	v_mfma_f32_32x32x16_bf16 v[16:31], v[4:7], v[102:105], v[16:31]
	s_waitcnt lgkmcnt(0)
	v_mfma_f32_32x32x16_bf16 v[16:31], v[0:3], v[98:101], v[16:31]
	ds_read_b128 v[0:3], v204 offset:96
	s_waitcnt lgkmcnt(0)
	v_mfma_f32_32x32x16_bf16 v[16:31], v[0:3], v[106:109], v[16:31]
	ds_read_b128 v[0:3], v205
	ds_read_b128 v[52:55], v205 offset:32
	s_waitcnt lgkmcnt(1)
	v_mfma_f32_32x32x16_bf16 v[0:15], v[0:3], v[48:51], 0
	s_waitcnt lgkmcnt(0)
	v_mfma_f32_32x32x16_bf16 v[0:15], v[52:55], v[102:105], v[0:15]
	ds_read_b128 v[52:55], v205 offset:64
	s_waitcnt lgkmcnt(0)
	v_mfma_f32_32x32x16_bf16 v[0:15], v[52:55], v[98:101], v[0:15]
	ds_read_b128 v[52:55], v205 offset:96
	s_waitcnt lgkmcnt(0)
	v_mfma_f32_32x32x16_bf16 v[0:15], v[52:55], v[106:109], v[0:15]
	ds_read_b128 v[52:55], v206
	ds_read_b128 v[110:113], v206 offset:32
	s_waitcnt lgkmcnt(1)
	v_mfma_f32_32x32x16_bf16 v[48:63], v[52:55], v[48:51], 0
	s_waitcnt lgkmcnt(0)
	v_mfma_f32_32x32x16_bf16 v[48:63], v[110:113], v[102:105], v[48:63]
	ds_read_b128 v[102:105], v206 offset:64
	s_waitcnt lgkmcnt(0)
	v_mfma_f32_32x32x16_bf16 v[48:63], v[102:105], v[98:101], v[48:63]
	ds_read_b128 v[98:101], v206 offset:96
	s_waitcnt lgkmcnt(0)
	v_mfma_f32_32x32x16_bf16 v[48:63], v[98:101], v[106:109], v[48:63]
	s_cbranch_vccz .LBB0_346
	v_cndmask_b32_e64 v98, v212, v64, s[2:3]
	v_cndmask_b32_e64 v105, v65, v212, s[4:5]
	v_cndmask_b32_e64 v104, v212, v66, s[6:7]
	v_cndmask_b32_e64 v103, v212, v67, s[8:9]
	v_cndmask_b32_e64 v102, v212, v68, s[10:11]
	v_cndmask_b32_e64 v101, v212, v69, s[12:13]
	v_cndmask_b32_e64 v100, v212, v70, s[14:15]
	v_cndmask_b32_e64 v99, v212, v71, s[16:17]
	v_cndmask_b32_e64 v71, v212, v72, s[18:19]
	v_cndmask_b32_e64 v70, v212, v73, s[20:21]
	v_cndmask_b32_e64 v69, v212, v74, s[22:23]
	v_cndmask_b32_e64 v68, v212, v75, s[24:25]
	v_cndmask_b32_e64 v67, v212, v76, s[26:27]
	v_cndmask_b32_e64 v66, v212, v77, s[28:29]
	v_cndmask_b32_e64 v65, v212, v78, s[30:31]
	v_cndmask_b32_e64 v64, v212, v79, s[34:35]
	s_branch .LBB0_347
